# 16-byte GEMM epilogue stores issued write-through (sc1) so the XCD leader's L2 write-back at the grid barrier has less to flush
# baseline (speedup 1.0000x reference)
.Lbrp_skip_0:
	s_waitcnt vmcnt(0) lgkmcnt(0)
	v_lshlrev_b32_e32 v146, 16, v140
	v_and_b32_e32 v147, 0xffff0000, v140
	v_lshlrev_b32_e32 v140, 16, v141
	v_and_b32_e32 v141, 0xffff0000, v141
	v_lshlrev_b32_e32 v148, 16, v142
	v_and_b32_e32 v149, 0xffff0000, v142
	v_lshlrev_b32_e32 v150, 16, v143
	v_and_b32_e32 v151, 0xffff0000, v143
	v_lshlrev_b64 v[180:181], 12, v[172:173]
	v_pk_mul_f32 v[140:141], v[126:127], v[140:141]
	v_pk_mul_f32 v[142:143], v[124:125], v[146:147]
	v_pk_mul_f32 v[146:147], v[122:123], v[150:151]
	v_pk_mul_f32 v[148:149], v[120:121], v[148:149]
	s_cmp_lt_i32 s93, 7
	s_mov_b64 s[10:11], -1
	s_cbranch_scc1 .LBB0_603
	s_cmp_lg_u32 s93, 7
	s_cbranch_scc0 .LBB0_600
	v_lshlrev_b32_e32 v150, 16, v132
	v_and_b32_e32 v151, 0xffff0000, v132
	v_pk_add_f32 v[150:151], v[142:143], v[150:151]
	v_lshlrev_b32_e32 v192, 16, v135
	v_and_b32_e32 v193, 0xffff0000, v135
	v_pk_add_f32 v[196:197], v[146:147], v[192:193]
	v_cvt_pk_bf16_f32 v192, v150, v151
	v_lshl_add_u64 v[150:151], s[18:19], 0, v[180:181]
	v_lshlrev_b32_e32 v154, 16, v133
	v_and_b32_e32 v155, 0xffff0000, v133
	v_lshlrev_b32_e32 v182, 16, v134
	v_and_b32_e32 v183, 0xffff0000, v134
	v_lshl_add_u64 v[150:151], v[174:175], 1, v[150:151]
	v_pk_add_f32 v[154:155], v[140:141], v[154:155]
	v_pk_add_f32 v[182:183], v[148:149], v[182:183]
	v_add_co_u32_e32 v150, vcc, 0xbf00000, v150
	v_cvt_pk_bf16_f32 v193, v154, v155
	v_cvt_pk_bf16_f32 v194, v182, v183
	v_cvt_pk_bf16_f32 v195, v196, v197
	v_addc_co_u32_e32 v151, vcc, 0, v151, vcc
	flat_store_dwordx4 v[150:151], v[192:195] offset:2048 sc1
	s_mov_b64 s[10:11], 0
.LBB0_600:
	s_andn2_b64 vcc, exec, s[10:11]
	s_cbranch_vccnz .LBB0_602
	v_readlane_b32 s10, v254, 35
	v_readlane_b32 s11, v254, 36
	v_cvt_pk_bf16_f32 v192, v142, v143
	v_cvt_pk_bf16_f32 v193, v140, v141
	v_lshl_add_u64 v[150:151], s[10:11], 0, v[180:181]
	v_cvt_pk_bf16_f32 v194, v148, v149
	v_cvt_pk_bf16_f32 v195, v146, v147
	v_lshl_add_u64 v[150:151], v[174:175], 1, v[150:151]
	flat_store_dwordx4 v[150:151], v[192:195] sc1

.LBB0_603:
	s_andn2_b64 vcc, exec, s[10:11]
	s_cbranch_vccnz .LBB0_605
	v_cvt_pk_bf16_f32 v192, v142, v143
	v_cvt_pk_bf16_f32 v193, v140, v141
	v_cvt_pk_bf16_f32 v194, v148, v149
	v_cvt_pk_bf16_f32 v195, v146, v147
	flat_store_dwordx4 v[144:145], v[192:195] sc1

.LBB0_610:
	v_lshl_add_u64 v[140:141], s[18:19], 0, v[180:181]
	v_lshl_add_u64 v[140:141], v[140:141], 0, v[182:183]
	v_cvt_pk_bf16_f32 v136, v144, v145
	v_cvt_pk_bf16_f32 v137, v146, v147
	v_cvt_pk_bf16_f32 v138, v148, v149
	v_cvt_pk_bf16_f32 v139, v150, v151
	v_lshl_add_u64 v[140:141], v[140:141], 0, v[176:177]
	flat_store_dwordx4 v[140:141], v[136:139] offset:256 sc1
	v_or_b32_e32 v146, 16, v172
	s_movk_i32 s10, 0x1800
	v_mov_b64_e32 v[136:137], s[44:45]
	v_mad_i64_i32 v[136:137], s[10:11], v146, s10, v[136:137]
	v_lshl_add_u64 v[136:137], v[136:137], 0, s[2:3]
	v_lshl_add_u64 v[136:137], v[136:137], 0, v[176:177]
	v_ashrrev_i32_e32 v147, 31, v146
	v_readlane_b32 s10, v254, 43
	v_lshlrev_b64 v[178:179], 11, v[146:147]
	v_readlane_b32 s11, v254, 44
	s_and_b64 vcc, exec, s[8:9]
	s_nop 0
	v_lshl_add_u64 v[138:139], s[10:11], 0, v[178:179]
	v_lshl_add_u64 v[144:145], v[138:139], 0, v[176:177]
	s_cbranch_vccnz .LBB0_612

.LBB0_614:
	v_lshlrev_b64 v[180:181], 12, v[146:147]
	v_mov_b64_e32 v[140:141], v[226:227]
	v_mov_b64_e32 v[142:143], v[228:229]
	v_mov_b64_e32 v[136:137], v[230:231]
	v_mov_b64_e32 v[138:139], v[232:233]
	v_mov_b64_e32 v[132:133], v[234:235]
	v_mov_b64_e32 v[134:135], v[236:237]
	v_mov_b64_e32 v[128:129], v[238:239]
	v_mov_b64_e32 v[130:131], v[240:241]
	v_lshlrev_b32_e32 v146, 16, v140
	v_and_b32_e32 v147, 0xffff0000, v140
	v_lshlrev_b32_e32 v140, 16, v141
	v_and_b32_e32 v141, 0xffff0000, v141
	v_lshlrev_b32_e32 v148, 16, v142
	v_and_b32_e32 v149, 0xffff0000, v142
	v_lshlrev_b32_e32 v150, 16, v143
	v_and_b32_e32 v151, 0xffff0000, v143
	v_pk_mul_f32 v[140:141], v[110:111], v[140:141]
	v_pk_mul_f32 v[142:143], v[108:109], v[146:147]
	v_pk_mul_f32 v[146:147], v[106:107], v[150:151]
	v_pk_mul_f32 v[148:149], v[104:105], v[148:149]
	s_cmp_lt_i32 s93, 7
	s_mov_b64 s[10:11], -1
	s_cbranch_scc1 .LBB0_620
	s_cmp_lg_u32 s93, 7
	s_cbranch_scc0 .LBB0_617
	v_lshlrev_b32_e32 v150, 16, v132
	v_and_b32_e32 v151, 0xffff0000, v132
	v_pk_add_f32 v[150:151], v[142:143], v[150:151]
	v_lshlrev_b32_e32 v192, 16, v135
	v_and_b32_e32 v193, 0xffff0000, v135
	v_pk_add_f32 v[196:197], v[146:147], v[192:193]
	v_cvt_pk_bf16_f32 v192, v150, v151
	v_lshl_add_u64 v[150:151], s[18:19], 0, v[180:181]
	v_lshlrev_b32_e32 v154, 16, v133
	v_and_b32_e32 v155, 0xffff0000, v133
	v_lshlrev_b32_e32 v182, 16, v134
	v_and_b32_e32 v183, 0xffff0000, v134
	v_lshl_add_u64 v[150:151], v[174:175], 1, v[150:151]
	v_pk_add_f32 v[154:155], v[140:141], v[154:155]
	v_pk_add_f32 v[182:183], v[148:149], v[182:183]
	v_add_co_u32_e32 v150, vcc, 0xbf00000, v150
	v_cvt_pk_bf16_f32 v193, v154, v155
	v_cvt_pk_bf16_f32 v194, v182, v183
	v_cvt_pk_bf16_f32 v195, v196, v197
	v_addc_co_u32_e32 v151, vcc, 0, v151, vcc
	flat_store_dwordx4 v[150:151], v[192:195] offset:2048 sc1
	s_mov_b64 s[10:11], 0

.LBB0_627:
	v_lshl_add_u64 v[140:141], s[18:19], 0, v[180:181]
	v_lshl_add_u64 v[140:141], v[140:141], 0, v[182:183]
	v_cvt_pk_bf16_f32 v136, v144, v145
	v_cvt_pk_bf16_f32 v137, v146, v147
	v_cvt_pk_bf16_f32 v138, v148, v149
	v_cvt_pk_bf16_f32 v139, v150, v151
	v_lshl_add_u64 v[140:141], v[140:141], 0, v[176:177]
	flat_store_dwordx4 v[140:141], v[136:139] offset:256 sc1
	v_or_b32_e32 v146, 32, v172
	s_movk_i32 s10, 0x1800
	v_mov_b64_e32 v[136:137], s[44:45]
	v_mad_i64_i32 v[136:137], s[10:11], v146, s10, v[136:137]
	v_lshl_add_u64 v[136:137], v[136:137], 0, s[2:3]
	v_lshl_add_u64 v[136:137], v[136:137], 0, v[176:177]
	flat_load_dwordx4 v[140:143], v[136:137]
	v_ashrrev_i32_e32 v147, 31, v146
	v_readlane_b32 s10, v254, 43
	v_lshlrev_b64 v[178:179], 11, v[146:147]
	v_readlane_b32 s11, v254, 44
	s_and_b64 vcc, exec, s[8:9]
	s_nop 0
	v_lshl_add_u64 v[138:139], s[10:11], 0, v[178:179]
	v_lshl_add_u64 v[144:145], v[138:139], 0, v[176:177]
	s_cbranch_vccnz .LBB0_629
	flat_load_dwordx4 v[132:135], v[144:145]

.Lbrp_skip_2:
	s_waitcnt vmcnt(0) lgkmcnt(0)
	v_lshlrev_b32_e32 v146, 16, v140
	v_and_b32_e32 v147, 0xffff0000, v140
	v_lshlrev_b32_e32 v140, 16, v141
	v_and_b32_e32 v141, 0xffff0000, v141
	v_lshlrev_b32_e32 v148, 16, v142
	v_and_b32_e32 v149, 0xffff0000, v142
	v_lshlrev_b32_e32 v150, 16, v143
	v_and_b32_e32 v151, 0xffff0000, v143
	v_pk_mul_f32 v[140:141], v[94:95], v[140:141]
	v_pk_mul_f32 v[142:143], v[92:93], v[146:147]
	v_pk_mul_f32 v[146:147], v[90:91], v[150:151]
	v_pk_mul_f32 v[148:149], v[88:89], v[148:149]
	s_cmp_lt_i32 s93, 7
	s_mov_b64 s[10:11], -1
	s_cbranch_scc1 .LBB0_637
	s_cmp_lg_u32 s93, 7
	s_cbranch_scc0 .LBB0_634
	v_lshlrev_b32_e32 v150, 16, v132
	v_and_b32_e32 v151, 0xffff0000, v132
	v_pk_add_f32 v[150:151], v[142:143], v[150:151]
	v_lshlrev_b32_e32 v192, 16, v135
	v_and_b32_e32 v193, 0xffff0000, v135
	v_pk_add_f32 v[196:197], v[146:147], v[192:193]
	v_cvt_pk_bf16_f32 v192, v150, v151
	v_lshl_add_u64 v[150:151], s[18:19], 0, v[180:181]
	v_lshlrev_b32_e32 v154, 16, v133
	v_and_b32_e32 v155, 0xffff0000, v133
	v_lshlrev_b32_e32 v182, 16, v134
	v_and_b32_e32 v183, 0xffff0000, v134
	v_lshl_add_u64 v[150:151], v[174:175], 1, v[150:151]
	v_pk_add_f32 v[154:155], v[140:141], v[154:155]
	v_pk_add_f32 v[182:183], v[148:149], v[182:183]
	v_add_co_u32_e32 v150, vcc, 0xbf00000, v150
	v_cvt_pk_bf16_f32 v193, v154, v155
	v_cvt_pk_bf16_f32 v194, v182, v183
	v_cvt_pk_bf16_f32 v195, v196, v197
	v_addc_co_u32_e32 v151, vcc, 0, v151, vcc
	flat_store_dwordx4 v[150:151], v[192:195] offset:2048 sc1
	s_mov_b64 s[10:11], 0

.LBB0_644:
	v_lshl_add_u64 v[140:141], s[18:19], 0, v[180:181]
	v_lshl_add_u64 v[140:141], v[140:141], 0, v[182:183]
	v_cvt_pk_bf16_f32 v136, v144, v145
	v_cvt_pk_bf16_f32 v137, v146, v147
	v_cvt_pk_bf16_f32 v138, v148, v149
	v_cvt_pk_bf16_f32 v139, v150, v151
	v_lshl_add_u64 v[140:141], v[140:141], 0, v[176:177]
	flat_store_dwordx4 v[140:141], v[136:139] offset:256 sc1
	v_or_b32_e32 v146, 48, v172
	s_movk_i32 s10, 0x1800
	v_mov_b64_e32 v[136:137], s[44:45]
	v_mad_i64_i32 v[136:137], s[10:11], v146, s10, v[136:137]
	v_lshl_add_u64 v[136:137], v[136:137], 0, s[2:3]
	v_lshl_add_u64 v[136:137], v[136:137], 0, v[176:177]
	v_ashrrev_i32_e32 v147, 31, v146
	v_readlane_b32 s10, v254, 43
	v_lshlrev_b64 v[178:179], 11, v[146:147]
	v_readlane_b32 s11, v254, 44
	s_and_b64 vcc, exec, s[8:9]
	s_nop 0
	v_lshl_add_u64 v[138:139], s[10:11], 0, v[178:179]
	v_lshl_add_u64 v[144:145], v[138:139], 0, v[176:177]
	s_cbranch_vccnz .LBB0_646

.LBB0_648:
	v_lshlrev_b64 v[180:181], 12, v[146:147]
	v_mov_b64_e32 v[140:141], v[226:227]
	v_mov_b64_e32 v[142:143], v[228:229]
	v_mov_b64_e32 v[136:137], v[230:231]
	v_mov_b64_e32 v[138:139], v[232:233]
	v_mov_b64_e32 v[132:133], v[234:235]
	v_mov_b64_e32 v[134:135], v[236:237]
	v_mov_b64_e32 v[128:129], v[238:239]
	v_mov_b64_e32 v[130:131], v[240:241]
	v_lshlrev_b32_e32 v146, 16, v140
	v_and_b32_e32 v147, 0xffff0000, v140
	v_lshlrev_b32_e32 v140, 16, v141
	v_and_b32_e32 v141, 0xffff0000, v141
	v_lshlrev_b32_e32 v148, 16, v142
	v_and_b32_e32 v149, 0xffff0000, v142
	v_lshlrev_b32_e32 v150, 16, v143
	v_and_b32_e32 v151, 0xffff0000, v143
	v_pk_mul_f32 v[140:141], v[78:79], v[140:141]
	v_pk_mul_f32 v[142:143], v[76:77], v[146:147]
	v_pk_mul_f32 v[146:147], v[74:75], v[150:151]
	v_pk_mul_f32 v[148:149], v[72:73], v[148:149]
	s_cmp_lt_i32 s93, 7
	s_mov_b64 s[10:11], -1
	s_cbranch_scc1 .LBB0_654
	s_cmp_lg_u32 s93, 7
	s_cbranch_scc0 .LBB0_651
	v_lshlrev_b32_e32 v150, 16, v132
	v_and_b32_e32 v151, 0xffff0000, v132
	v_pk_add_f32 v[150:151], v[142:143], v[150:151]
	v_lshlrev_b32_e32 v192, 16, v135
	v_and_b32_e32 v193, 0xffff0000, v135
	v_pk_add_f32 v[196:197], v[146:147], v[192:193]
	v_cvt_pk_bf16_f32 v192, v150, v151
	v_lshl_add_u64 v[150:151], s[18:19], 0, v[180:181]
	v_lshlrev_b32_e32 v154, 16, v133
	v_and_b32_e32 v155, 0xffff0000, v133
	v_lshlrev_b32_e32 v182, 16, v134
	v_and_b32_e32 v183, 0xffff0000, v134
	v_lshl_add_u64 v[150:151], v[174:175], 1, v[150:151]
	v_pk_add_f32 v[154:155], v[140:141], v[154:155]
	v_pk_add_f32 v[182:183], v[148:149], v[182:183]
	v_add_co_u32_e32 v150, vcc, 0xbf00000, v150
	v_cvt_pk_bf16_f32 v193, v154, v155
	v_cvt_pk_bf16_f32 v194, v182, v183
	v_cvt_pk_bf16_f32 v195, v196, v197
	v_addc_co_u32_e32 v151, vcc, 0, v151, vcc
	flat_store_dwordx4 v[150:151], v[192:195] offset:2048 sc1
	s_mov_b64 s[10:11], 0

.LBB0_661:
	v_lshl_add_u64 v[140:141], s[18:19], 0, v[180:181]
	v_lshl_add_u64 v[140:141], v[140:141], 0, v[182:183]
	v_cvt_pk_bf16_f32 v136, v144, v145
	v_cvt_pk_bf16_f32 v137, v146, v147
	v_cvt_pk_bf16_f32 v138, v148, v149
	v_cvt_pk_bf16_f32 v139, v150, v151
	v_lshl_add_u64 v[140:141], v[140:141], 0, v[176:177]
	flat_store_dwordx4 v[140:141], v[136:139] offset:256 sc1
	v_add_u32_e32 v146, 0x80, v172
	s_movk_i32 s10, 0x1800
	v_mov_b64_e32 v[136:137], s[44:45]
	v_mad_i64_i32 v[136:137], s[10:11], v146, s10, v[136:137]
	v_lshl_add_u64 v[136:137], v[136:137], 0, s[2:3]
	v_lshl_add_u64 v[136:137], v[136:137], 0, v[176:177]
	flat_load_dwordx4 v[140:143], v[136:137]
	v_ashrrev_i32_e32 v147, 31, v146
	v_readlane_b32 s10, v254, 43
	v_lshlrev_b64 v[178:179], 11, v[146:147]
	v_readlane_b32 s11, v254, 44
	s_and_b64 vcc, exec, s[8:9]
	s_nop 0
	v_lshl_add_u64 v[138:139], s[10:11], 0, v[178:179]
	v_lshl_add_u64 v[144:145], v[138:139], 0, v[176:177]
	s_cbranch_vccnz .LBB0_663
	flat_load_dwordx4 v[132:135], v[144:145]

.Lbrp_skip_4:
	s_waitcnt vmcnt(0) lgkmcnt(0)
	v_lshlrev_b32_e32 v146, 16, v140
	v_and_b32_e32 v147, 0xffff0000, v140
	v_lshlrev_b32_e32 v140, 16, v141
	v_and_b32_e32 v141, 0xffff0000, v141
	v_lshlrev_b32_e32 v148, 16, v142
	v_and_b32_e32 v149, 0xffff0000, v142
	v_lshlrev_b32_e32 v150, 16, v143
	v_and_b32_e32 v151, 0xffff0000, v143
	v_pk_mul_f32 v[140:141], v[62:63], v[140:141]
	v_pk_mul_f32 v[142:143], v[60:61], v[146:147]
	v_pk_mul_f32 v[146:147], v[58:59], v[150:151]
	v_pk_mul_f32 v[148:149], v[56:57], v[148:149]
	s_cmp_lt_i32 s93, 7
	s_mov_b64 s[10:11], -1
	s_cbranch_scc1 .LBB0_671
	s_cmp_lg_u32 s93, 7
	s_cbranch_scc0 .LBB0_668
	v_lshlrev_b32_e32 v150, 16, v132
	v_and_b32_e32 v151, 0xffff0000, v132
	v_pk_add_f32 v[150:151], v[142:143], v[150:151]
	v_lshlrev_b32_e32 v192, 16, v135
	v_and_b32_e32 v193, 0xffff0000, v135
	v_pk_add_f32 v[196:197], v[146:147], v[192:193]
	v_cvt_pk_bf16_f32 v192, v150, v151
	v_lshl_add_u64 v[150:151], s[18:19], 0, v[180:181]
	v_lshlrev_b32_e32 v154, 16, v133
	v_and_b32_e32 v155, 0xffff0000, v133
	v_lshlrev_b32_e32 v182, 16, v134
	v_and_b32_e32 v183, 0xffff0000, v134
	v_lshl_add_u64 v[150:151], v[174:175], 1, v[150:151]
	v_pk_add_f32 v[154:155], v[140:141], v[154:155]
	v_pk_add_f32 v[182:183], v[148:149], v[182:183]
	v_add_co_u32_e32 v150, vcc, 0xbf00000, v150
	v_cvt_pk_bf16_f32 v193, v154, v155
	v_cvt_pk_bf16_f32 v194, v182, v183
	v_cvt_pk_bf16_f32 v195, v196, v197
	v_addc_co_u32_e32 v151, vcc, 0, v151, vcc
	flat_store_dwordx4 v[150:151], v[192:195] offset:2048 sc1
	s_mov_b64 s[10:11], 0

.LBB0_678:
	v_lshl_add_u64 v[140:141], s[18:19], 0, v[180:181]
	v_lshl_add_u64 v[140:141], v[140:141], 0, v[182:183]
	v_cvt_pk_bf16_f32 v136, v144, v145
	v_cvt_pk_bf16_f32 v137, v146, v147
	v_cvt_pk_bf16_f32 v138, v148, v149
	v_cvt_pk_bf16_f32 v139, v150, v151
	v_lshl_add_u64 v[140:141], v[140:141], 0, v[176:177]
	flat_store_dwordx4 v[140:141], v[136:139] offset:256 sc1
	v_add_u32_e32 v146, 0x90, v172
	s_movk_i32 s10, 0x1800
	v_mov_b64_e32 v[136:137], s[44:45]
	v_mad_i64_i32 v[136:137], s[10:11], v146, s10, v[136:137]
	v_lshl_add_u64 v[136:137], v[136:137], 0, s[2:3]
	v_lshl_add_u64 v[136:137], v[136:137], 0, v[176:177]
	v_ashrrev_i32_e32 v147, 31, v146
	v_readlane_b32 s10, v254, 43
	v_lshlrev_b64 v[178:179], 11, v[146:147]
	v_readlane_b32 s11, v254, 44
	s_and_b64 vcc, exec, s[8:9]
	s_nop 0
	v_lshl_add_u64 v[138:139], s[10:11], 0, v[178:179]
	v_lshl_add_u64 v[144:145], v[138:139], 0, v[176:177]
	s_cbranch_vccnz .LBB0_680

.LBB0_682:
	v_lshlrev_b64 v[180:181], 12, v[146:147]
	v_mov_b64_e32 v[140:141], v[226:227]
	v_mov_b64_e32 v[142:143], v[228:229]
	v_mov_b64_e32 v[136:137], v[230:231]
	v_mov_b64_e32 v[138:139], v[232:233]
	v_mov_b64_e32 v[132:133], v[234:235]
	v_mov_b64_e32 v[134:135], v[236:237]
	v_mov_b64_e32 v[128:129], v[238:239]
	v_mov_b64_e32 v[130:131], v[240:241]
	v_lshlrev_b32_e32 v146, 16, v140
	v_and_b32_e32 v147, 0xffff0000, v140
	v_lshlrev_b32_e32 v140, 16, v141
	v_and_b32_e32 v141, 0xffff0000, v141
	v_lshlrev_b32_e32 v148, 16, v142
	v_and_b32_e32 v149, 0xffff0000, v142
	v_lshlrev_b32_e32 v150, 16, v143
	v_and_b32_e32 v151, 0xffff0000, v143
	v_pk_mul_f32 v[140:141], v[46:47], v[140:141]
	v_pk_mul_f32 v[142:143], v[44:45], v[146:147]
	v_pk_mul_f32 v[146:147], v[42:43], v[150:151]
	v_pk_mul_f32 v[148:149], v[40:41], v[148:149]
	s_cmp_lt_i32 s93, 7
	s_mov_b64 s[10:11], -1
	s_cbranch_scc1 .LBB0_688
	s_cmp_lg_u32 s93, 7
	s_cbranch_scc0 .LBB0_685
	v_lshlrev_b32_e32 v150, 16, v132
	v_and_b32_e32 v151, 0xffff0000, v132
	v_pk_add_f32 v[150:151], v[142:143], v[150:151]
	v_lshlrev_b32_e32 v192, 16, v135
	v_and_b32_e32 v193, 0xffff0000, v135
	v_pk_add_f32 v[196:197], v[146:147], v[192:193]
	v_cvt_pk_bf16_f32 v192, v150, v151
	v_lshl_add_u64 v[150:151], s[18:19], 0, v[180:181]
	v_lshlrev_b32_e32 v154, 16, v133
	v_and_b32_e32 v155, 0xffff0000, v133
	v_lshlrev_b32_e32 v182, 16, v134
	v_and_b32_e32 v183, 0xffff0000, v134
	v_lshl_add_u64 v[150:151], v[174:175], 1, v[150:151]
	v_pk_add_f32 v[154:155], v[140:141], v[154:155]
	v_pk_add_f32 v[182:183], v[148:149], v[182:183]
	v_add_co_u32_e32 v150, vcc, 0xbf00000, v150
	v_cvt_pk_bf16_f32 v193, v154, v155
	v_cvt_pk_bf16_f32 v194, v182, v183
	v_cvt_pk_bf16_f32 v195, v196, v197
	v_addc_co_u32_e32 v151, vcc, 0, v151, vcc
	flat_store_dwordx4 v[150:151], v[192:195] offset:2048 sc1
	s_mov_b64 s[10:11], 0

.LBB0_695:
	v_lshl_add_u64 v[140:141], s[18:19], 0, v[180:181]
	v_lshl_add_u64 v[140:141], v[140:141], 0, v[182:183]
	v_cvt_pk_bf16_f32 v136, v144, v145
	v_cvt_pk_bf16_f32 v137, v146, v147
	v_cvt_pk_bf16_f32 v138, v148, v149
	v_cvt_pk_bf16_f32 v139, v150, v151
	v_lshl_add_u64 v[140:141], v[140:141], 0, v[176:177]
	flat_store_dwordx4 v[140:141], v[136:139] offset:256 sc1
	v_add_u32_e32 v146, 0xa0, v172
	s_movk_i32 s10, 0x1800
	v_mov_b64_e32 v[136:137], s[44:45]
	v_mad_i64_i32 v[136:137], s[10:11], v146, s10, v[136:137]
	v_lshl_add_u64 v[136:137], v[136:137], 0, s[2:3]
	v_lshl_add_u64 v[136:137], v[136:137], 0, v[176:177]
	flat_load_dwordx4 v[140:143], v[136:137]
	v_ashrrev_i32_e32 v147, 31, v146
	v_readlane_b32 s10, v254, 43
	v_lshlrev_b64 v[178:179], 11, v[146:147]
	v_readlane_b32 s11, v254, 44
	s_and_b64 vcc, exec, s[8:9]
	s_nop 0
	v_lshl_add_u64 v[138:139], s[10:11], 0, v[178:179]
	v_lshl_add_u64 v[144:145], v[138:139], 0, v[176:177]
	s_cbranch_vccnz .LBB0_697
	flat_load_dwordx4 v[132:135], v[144:145]

.Lbrp_skip_6:
	s_waitcnt vmcnt(0) lgkmcnt(0)
	v_lshlrev_b32_e32 v146, 16, v140
	v_and_b32_e32 v147, 0xffff0000, v140
	v_lshlrev_b32_e32 v140, 16, v141
	v_and_b32_e32 v141, 0xffff0000, v141
	v_lshlrev_b32_e32 v148, 16, v142
	v_and_b32_e32 v149, 0xffff0000, v142
	v_lshlrev_b32_e32 v150, 16, v143
	v_and_b32_e32 v151, 0xffff0000, v143
	v_pk_mul_f32 v[140:141], v[30:31], v[140:141]
	v_pk_mul_f32 v[142:143], v[28:29], v[146:147]
	v_pk_mul_f32 v[146:147], v[26:27], v[150:151]
	v_pk_mul_f32 v[148:149], v[24:25], v[148:149]
	s_cmp_lt_i32 s93, 7
	s_mov_b64 s[10:11], -1
	s_cbranch_scc1 .LBB0_705
	s_cmp_lg_u32 s93, 7
	s_cbranch_scc0 .LBB0_702
	v_lshlrev_b32_e32 v150, 16, v132
	v_and_b32_e32 v151, 0xffff0000, v132
	v_pk_add_f32 v[150:151], v[142:143], v[150:151]
	v_lshlrev_b32_e32 v192, 16, v135
	v_and_b32_e32 v193, 0xffff0000, v135
	v_pk_add_f32 v[196:197], v[146:147], v[192:193]
	v_cvt_pk_bf16_f32 v192, v150, v151
	v_lshl_add_u64 v[150:151], s[18:19], 0, v[180:181]
	v_lshlrev_b32_e32 v154, 16, v133
	v_and_b32_e32 v155, 0xffff0000, v133
	v_lshlrev_b32_e32 v182, 16, v134
	v_and_b32_e32 v183, 0xffff0000, v134
	v_lshl_add_u64 v[150:151], v[174:175], 1, v[150:151]
	v_pk_add_f32 v[154:155], v[140:141], v[154:155]
	v_pk_add_f32 v[182:183], v[148:149], v[182:183]
	v_add_co_u32_e32 v150, vcc, 0xbf00000, v150
	v_cvt_pk_bf16_f32 v193, v154, v155
	v_cvt_pk_bf16_f32 v194, v182, v183
	v_cvt_pk_bf16_f32 v195, v196, v197
	v_addc_co_u32_e32 v151, vcc, 0, v151, vcc
	flat_store_dwordx4 v[150:151], v[192:195] offset:2048 sc1
	s_mov_b64 s[10:11], 0

.LBB0_712:
	v_lshl_add_u64 v[140:141], s[18:19], 0, v[180:181]
	v_lshl_add_u64 v[140:141], v[140:141], 0, v[182:183]
	v_cvt_pk_bf16_f32 v136, v144, v145
	v_cvt_pk_bf16_f32 v137, v146, v147
	v_cvt_pk_bf16_f32 v138, v148, v149
	v_cvt_pk_bf16_f32 v139, v150, v151
	v_lshl_add_u64 v[140:141], v[140:141], 0, v[176:177]
	flat_store_dwordx4 v[140:141], v[136:139] offset:256 sc1
	v_add_u32_e32 v146, 0xb0, v172
	s_movk_i32 s10, 0x1800
	v_mov_b64_e32 v[136:137], s[44:45]
	v_mad_i64_i32 v[136:137], s[10:11], v146, s10, v[136:137]
	v_lshl_add_u64 v[136:137], v[136:137], 0, s[2:3]
	v_lshl_add_u64 v[136:137], v[136:137], 0, v[176:177]
	v_ashrrev_i32_e32 v147, 31, v146
	v_readlane_b32 s10, v254, 43
	v_lshlrev_b64 v[148:149], 11, v[146:147]
	v_readlane_b32 s11, v254, 44
	s_and_b64 vcc, exec, s[8:9]
	s_nop 0
	v_lshl_add_u64 v[138:139], s[10:11], 0, v[148:149]
	v_lshl_add_u64 v[144:145], v[138:139], 0, v[176:177]
	s_cbranch_vccnz .LBB0_714

.LBB0_716:
	v_lshlrev_b64 v[150:151], 12, v[146:147]
	v_mov_b64_e32 v[140:141], v[226:227]
	v_mov_b64_e32 v[142:143], v[228:229]
	v_mov_b64_e32 v[136:137], v[230:231]
	v_mov_b64_e32 v[138:139], v[232:233]
	v_mov_b64_e32 v[132:133], v[234:235]
	v_mov_b64_e32 v[134:135], v[236:237]
	v_mov_b64_e32 v[128:129], v[238:239]
	v_mov_b64_e32 v[130:131], v[240:241]
	v_lshlrev_b32_e32 v146, 16, v140
	v_and_b32_e32 v147, 0xffff0000, v140
	v_lshlrev_b32_e32 v140, 16, v141
	v_and_b32_e32 v141, 0xffff0000, v141
	v_lshlrev_b32_e32 v154, 16, v142
	v_and_b32_e32 v155, 0xffff0000, v142
	v_lshlrev_b32_e32 v176, 16, v143
	v_and_b32_e32 v177, 0xffff0000, v143
	v_pk_mul_f32 v[140:141], v[14:15], v[140:141]
	v_pk_mul_f32 v[142:143], v[12:13], v[146:147]
	v_pk_mul_f32 v[146:147], v[10:11], v[176:177]
	v_pk_mul_f32 v[176:177], v[8:9], v[154:155]
	s_cmp_lt_i32 s93, 7
	s_mov_b64 s[8:9], -1
	s_cbranch_scc1 .LBB0_722
	s_cmp_lg_u32 s93, 7
	s_cbranch_scc0 .LBB0_719
	v_lshlrev_b32_e32 v154, 16, v132
	v_and_b32_e32 v155, 0xffff0000, v132
	v_lshlrev_b32_e32 v132, 16, v133
	v_and_b32_e32 v133, 0xffff0000, v133
	v_pk_add_f32 v[178:179], v[140:141], v[132:133]
	v_pk_add_f32 v[132:133], v[142:143], v[154:155]
	v_lshlrev_b32_e32 v154, 16, v134
	v_and_b32_e32 v155, 0xffff0000, v134
	v_lshlrev_b32_e32 v134, 16, v135
	v_and_b32_e32 v135, 0xffff0000, v135
	v_pk_add_f32 v[180:181], v[146:147], v[134:135]
	v_pk_add_f32 v[134:135], v[176:177], v[154:155]
	v_lshl_add_u64 v[154:155], s[18:19], 0, v[150:151]
	v_lshl_add_u64 v[154:155], v[174:175], 1, v[154:155]
	v_add_co_u32_e32 v154, vcc, 0xbf00000, v154
	v_cvt_pk_bf16_f32 v132, v132, v133
	v_cvt_pk_bf16_f32 v133, v178, v179
	v_cvt_pk_bf16_f32 v134, v134, v135
	v_cvt_pk_bf16_f32 v135, v180, v181
	v_addc_co_u32_e32 v155, vcc, 0, v155, vcc
	flat_store_dwordx4 v[154:155], v[132:135] offset:2048 sc1
	s_mov_b64 s[8:9], 0
.LBB0_719:
	s_andn2_b64 vcc, exec, s[8:9]
	s_cbranch_vccnz .LBB0_721
	v_readlane_b32 s8, v254, 35
	v_readlane_b32 s9, v254, 36
	v_cvt_pk_bf16_f32 v132, v142, v143
	v_cvt_pk_bf16_f32 v133, v140, v141
	v_lshl_add_u64 v[154:155], s[8:9], 0, v[150:151]
	v_cvt_pk_bf16_f32 v134, v176, v177
	v_cvt_pk_bf16_f32 v135, v146, v147
	v_lshl_add_u64 v[154:155], v[174:175], 1, v[154:155]
	flat_store_dwordx4 v[154:155], v[132:135] sc1

.LBB0_722:
	s_andn2_b64 vcc, exec, s[8:9]
	s_cbranch_vccnz .LBB0_724
	v_cvt_pk_bf16_f32 v132, v142, v143
	v_cvt_pk_bf16_f32 v133, v140, v141
	v_cvt_pk_bf16_f32 v134, v176, v177
	v_cvt_pk_bf16_f32 v135, v146, v147
	flat_store_dwordx4 v[144:145], v[132:135] sc1

.LBB0_729:
	v_lshl_add_u64 v[132:133], s[18:19], 0, v[150:151]
	v_lshl_add_u64 v[132:133], v[132:133], 0, v[176:177]
	v_cvt_pk_bf16_f32 v128, v140, v141
	v_cvt_pk_bf16_f32 v129, v142, v143
	v_cvt_pk_bf16_f32 v130, v144, v145
	v_cvt_pk_bf16_f32 v131, v146, v147
	v_lshl_add_u64 v[132:133], v[174:175], 1, v[132:133]
	flat_store_dwordx4 v[132:133], v[128:131] offset:256 sc1

.LBB0_1004:
	s_andn2_b64 vcc, exec, s[8:9]
	s_cbranch_vccnz .LBB0_535
	s_cmp_lt_i32 s93, 1
	s_mov_b64 s[8:9], -1
	s_cbranch_scc1 .LBB0_1136
	s_cmp_gt_i32 s93, 1
	s_cbranch_scc0 .LBB0_1133
	s_cmp_gt_i32 s14, 3
	s_cbranch_scc0 .LBB0_1130
	s_cmp_gt_u32 s14, 5
	s_cbranch_scc0 .LBB0_1127
	s_and_b32 s2, s40, 0xfffffc00
	s_cmp_lt_i32 s27, 16
	s_cselect_b64 s[12:13], -1, 0
	s_and_b64 s[8:9], s[12:13], exec
	s_cselect_b32 s64, s40, s2
	s_movk_i32 s2, 0x400
	s_cselect_b32 s66, 0x100, s2
	s_cmp_gt_u32 s14, 7
	s_mov_b64 s[8:9], -1
	s_cbranch_scc0 .LBB0_1124
	v_readlane_b32 s40, v254, 59
	s_cmp_gt_u32 s14, 11
	v_readlane_b32 s41, v254, 60
	s_cbranch_scc0 .LBB0_1121
	s_cmp_gt_u32 s14, 15
	s_cbranch_scc0 .LBB0_1118
	s_cmp_gt_u32 s14, 18
	s_cbranch_scc0 .LBB0_1051
	s_cmp_eq_u32 s14, 19
	s_cbranch_scc1 .LBB0_1015
	v_mul_f32_e32 v132, 0xbfb8aa3b, v124
	v_mul_f32_e32 v133, 0xbfb8aa3b, v125
	s_lshl_b32 s2, s14, 8
	v_mov_b64_e32 v[128:129], s[44:45]
	s_movk_i32 s20, 0x1800
	v_exp_f32_e32 v132, v132
	v_exp_f32_e32 v133, v133
	s_addk_i32 s2, 0xec00
	v_mad_i64_i32 v[130:131], s[8:9], v172, s20, v[128:129]
	s_lshl_b64 s[8:9], s[2:3], 1
	s_nop 0
	v_lshl_add_u64 v[130:131], v[130:131], 0, s[8:9]
	v_lshlrev_b32_e32 v152, 1, v186
	v_lshl_add_u64 v[134:135], v[130:131], 0, v[152:153]
	v_add_f32_e32 v130, 1.0, v132
	v_add_f32_e32 v131, 1.0, v133
	v_mul_f32_e32 v132, 0xbfb8aa3b, v126
	v_mul_f32_e32 v133, 0xbfb8aa3b, v127
	v_mul_f32_e32 v136, 0xbfb8aa3b, v120
	v_mul_f32_e32 v137, 0xbfb8aa3b, v121
	v_exp_f32_e32 v132, v132
	v_exp_f32_e32 v133, v133
	v_exp_f32_e32 v136, v136
	v_exp_f32_e32 v137, v137
	v_mul_f32_e32 v138, 0xbfb8aa3b, v122
	v_mul_f32_e32 v139, 0xbfb8aa3b, v123
	v_add_f32_e32 v132, 1.0, v132
	v_add_f32_e32 v133, 1.0, v133
	v_add_f32_e32 v136, 1.0, v136
	v_add_f32_e32 v137, 1.0, v137
	v_exp_f32_e32 v138, v138
	v_exp_f32_e32 v139, v139
	v_rcp_f32_e32 v130, v130
	v_rcp_f32_e32 v131, v131
	v_rcp_f32_e32 v132, v132
	v_rcp_f32_e32 v133, v133
	v_rcp_f32_e32 v136, v136
	v_rcp_f32_e32 v137, v137
	v_add_f32_e32 v138, 1.0, v138
	v_add_f32_e32 v139, 1.0, v139
	v_rcp_f32_e32 v138, v138
	v_rcp_f32_e32 v139, v139
	v_cvt_pk_bf16_f32 v130, v130, v131
	v_cvt_pk_bf16_f32 v131, v132, v133
	v_cvt_pk_bf16_f32 v132, v136, v137
	v_mul_f32_e32 v136, 0xbfb8aa3b, v116
	v_mul_f32_e32 v137, 0xbfb8aa3b, v117
	v_exp_f32_e32 v136, v136
	v_exp_f32_e32 v137, v137
	v_cvt_pk_bf16_f32 v133, v138, v139
	flat_store_dwordx4 v[134:135], v[130:133] sc1
	v_mul_f32_e32 v138, 0xbfb8aa3b, v114
	v_mul_f32_e32 v139, 0xbfb8aa3b, v115
	v_add_f32_e32 v130, 1.0, v136
	v_add_f32_e32 v131, 1.0, v137
	v_mul_f32_e32 v132, 0xbfb8aa3b, v118
	v_mul_f32_e32 v133, 0xbfb8aa3b, v119
	v_mul_f32_e32 v136, 0xbfb8aa3b, v112
	v_mul_f32_e32 v137, 0xbfb8aa3b, v113
	v_exp_f32_e32 v132, v132
	v_exp_f32_e32 v133, v133
	v_exp_f32_e32 v136, v136
	v_exp_f32_e32 v137, v137
	v_exp_f32_e32 v138, v138
	v_exp_f32_e32 v139, v139
	v_add_f32_e32 v132, 1.0, v132
	v_add_f32_e32 v133, 1.0, v133
	v_add_f32_e32 v136, 1.0, v136
	v_add_f32_e32 v137, 1.0, v137
	v_add_f32_e32 v138, 1.0, v138
	v_add_f32_e32 v139, 1.0, v139
	v_rcp_f32_e32 v130, v130
	v_rcp_f32_e32 v131, v131
	v_rcp_f32_e32 v132, v132
	v_rcp_f32_e32 v133, v133
	v_rcp_f32_e32 v136, v136
	v_rcp_f32_e32 v137, v137
	v_rcp_f32_e32 v138, v138
	v_rcp_f32_e32 v139, v139
	v_cvt_pk_bf16_f32 v130, v130, v131
	v_cvt_pk_bf16_f32 v131, v132, v133
	v_cvt_pk_bf16_f32 v132, v136, v137
	v_cvt_pk_bf16_f32 v133, v138, v139
	flat_store_dwordx4 v[134:135], v[130:133] offset:256 sc1
	v_mul_f32_e32 v136, 0xbfb8aa3b, v104
	v_mul_f32_e32 v137, 0xbfb8aa3b, v105
	v_mul_f32_e32 v132, 0xbfb8aa3b, v108
	v_mul_f32_e32 v133, 0xbfb8aa3b, v109
	v_exp_f32_e32 v132, v132
	v_exp_f32_e32 v133, v133
	v_or_b32_e32 v130, 16, v172
	v_mad_i64_i32 v[130:131], s[10:11], v130, s20, v[128:129]
	v_lshl_add_u64 v[130:131], v[130:131], 0, s[8:9]
	v_lshl_add_u64 v[134:135], v[130:131], 0, v[152:153]
	v_add_f32_e32 v130, 1.0, v132
	v_add_f32_e32 v131, 1.0, v133
	v_mul_f32_e32 v132, 0xbfb8aa3b, v110
	v_mul_f32_e32 v133, 0xbfb8aa3b, v111
	v_exp_f32_e32 v132, v132
	v_exp_f32_e32 v133, v133
	v_exp_f32_e32 v136, v136
	v_exp_f32_e32 v137, v137
	v_mul_f32_e32 v138, 0xbfb8aa3b, v106
	v_mul_f32_e32 v139, 0xbfb8aa3b, v107
	v_add_f32_e32 v132, 1.0, v132
	v_add_f32_e32 v133, 1.0, v133
	v_add_f32_e32 v136, 1.0, v136
	v_add_f32_e32 v137, 1.0, v137
	v_exp_f32_e32 v138, v138
	v_exp_f32_e32 v139, v139
	v_rcp_f32_e32 v130, v130
	v_rcp_f32_e32 v131, v131
	v_rcp_f32_e32 v132, v132
	v_rcp_f32_e32 v133, v133
	v_rcp_f32_e32 v136, v136
	v_rcp_f32_e32 v137, v137
	v_add_f32_e32 v138, 1.0, v138
	v_add_f32_e32 v139, 1.0, v139
	v_rcp_f32_e32 v138, v138
	v_rcp_f32_e32 v139, v139
	v_cvt_pk_bf16_f32 v130, v130, v131
	v_cvt_pk_bf16_f32 v131, v132, v133
	v_cvt_pk_bf16_f32 v132, v136, v137
	v_mul_f32_e32 v136, 0xbfb8aa3b, v100
	v_mul_f32_e32 v137, 0xbfb8aa3b, v101
	v_exp_f32_e32 v136, v136
	v_exp_f32_e32 v137, v137
	v_cvt_pk_bf16_f32 v133, v138, v139
	flat_store_dwordx4 v[134:135], v[130:133] sc1
	v_mul_f32_e32 v138, 0xbfb8aa3b, v98
	v_mul_f32_e32 v139, 0xbfb8aa3b, v99
	v_add_f32_e32 v130, 1.0, v136
	v_add_f32_e32 v131, 1.0, v137
	v_mul_f32_e32 v132, 0xbfb8aa3b, v102
	v_mul_f32_e32 v133, 0xbfb8aa3b, v103
	v_mul_f32_e32 v136, 0xbfb8aa3b, v96
	v_mul_f32_e32 v137, 0xbfb8aa3b, v97
	v_exp_f32_e32 v132, v132
	v_exp_f32_e32 v133, v133
	v_exp_f32_e32 v136, v136
	v_exp_f32_e32 v137, v137
	v_exp_f32_e32 v138, v138
	v_exp_f32_e32 v139, v139
	v_add_f32_e32 v132, 1.0, v132
	v_add_f32_e32 v133, 1.0, v133
	v_add_f32_e32 v136, 1.0, v136
	v_add_f32_e32 v137, 1.0, v137
	v_add_f32_e32 v138, 1.0, v138
	v_add_f32_e32 v139, 1.0, v139
	v_rcp_f32_e32 v130, v130
	v_rcp_f32_e32 v131, v131
	v_rcp_f32_e32 v132, v132
	v_rcp_f32_e32 v133, v133
	v_rcp_f32_e32 v136, v136
	v_rcp_f32_e32 v137, v137
	v_rcp_f32_e32 v138, v138
	v_rcp_f32_e32 v139, v139
	v_cvt_pk_bf16_f32 v130, v130, v131
	v_cvt_pk_bf16_f32 v131, v132, v133
	v_cvt_pk_bf16_f32 v132, v136, v137
	v_cvt_pk_bf16_f32 v133, v138, v139
	flat_store_dwordx4 v[134:135], v[130:133] offset:256 sc1
	v_mul_f32_e32 v136, 0xbfb8aa3b, v88
	v_mul_f32_e32 v137, 0xbfb8aa3b, v89
	v_mul_f32_e32 v132, 0xbfb8aa3b, v92
	v_mul_f32_e32 v133, 0xbfb8aa3b, v93
	v_exp_f32_e32 v132, v132
	v_exp_f32_e32 v133, v133
	v_or_b32_e32 v130, 32, v172
	v_mad_i64_i32 v[130:131], s[10:11], v130, s20, v[128:129]
	v_lshl_add_u64 v[130:131], v[130:131], 0, s[8:9]
	v_lshl_add_u64 v[134:135], v[130:131], 0, v[152:153]
	v_add_f32_e32 v130, 1.0, v132
	v_add_f32_e32 v131, 1.0, v133
	v_mul_f32_e32 v132, 0xbfb8aa3b, v94
	v_mul_f32_e32 v133, 0xbfb8aa3b, v95
	v_exp_f32_e32 v132, v132
	v_exp_f32_e32 v133, v133
	v_exp_f32_e32 v136, v136
	v_exp_f32_e32 v137, v137
	v_mul_f32_e32 v138, 0xbfb8aa3b, v90
	v_mul_f32_e32 v139, 0xbfb8aa3b, v91
	v_add_f32_e32 v132, 1.0, v132
	v_add_f32_e32 v133, 1.0, v133
	v_add_f32_e32 v136, 1.0, v136
	v_add_f32_e32 v137, 1.0, v137
	v_exp_f32_e32 v138, v138
	v_exp_f32_e32 v139, v139
	v_rcp_f32_e32 v130, v130
	v_rcp_f32_e32 v131, v131
	v_rcp_f32_e32 v132, v132
	v_rcp_f32_e32 v133, v133
	v_rcp_f32_e32 v136, v136
	v_rcp_f32_e32 v137, v137
	v_add_f32_e32 v138, 1.0, v138
	v_add_f32_e32 v139, 1.0, v139
	v_rcp_f32_e32 v138, v138
	v_rcp_f32_e32 v139, v139
	v_cvt_pk_bf16_f32 v130, v130, v131
	v_cvt_pk_bf16_f32 v131, v132, v133
	v_cvt_pk_bf16_f32 v132, v136, v137
	v_mul_f32_e32 v136, 0xbfb8aa3b, v84
	v_mul_f32_e32 v137, 0xbfb8aa3b, v85
	v_exp_f32_e32 v136, v136
	v_exp_f32_e32 v137, v137
	v_cvt_pk_bf16_f32 v133, v138, v139
	flat_store_dwordx4 v[134:135], v[130:133] sc1
	v_mul_f32_e32 v138, 0xbfb8aa3b, v82
	v_mul_f32_e32 v139, 0xbfb8aa3b, v83
	v_add_f32_e32 v130, 1.0, v136
	v_add_f32_e32 v131, 1.0, v137
	v_mul_f32_e32 v132, 0xbfb8aa3b, v86
	v_mul_f32_e32 v133, 0xbfb8aa3b, v87
	v_mul_f32_e32 v136, 0xbfb8aa3b, v80
	v_mul_f32_e32 v137, 0xbfb8aa3b, v81
	v_exp_f32_e32 v132, v132
	v_exp_f32_e32 v133, v133
	v_exp_f32_e32 v136, v136
	v_exp_f32_e32 v137, v137
	v_exp_f32_e32 v138, v138
	v_exp_f32_e32 v139, v139
	v_add_f32_e32 v132, 1.0, v132
	v_add_f32_e32 v133, 1.0, v133
	v_add_f32_e32 v136, 1.0, v136
	v_add_f32_e32 v137, 1.0, v137
	v_add_f32_e32 v138, 1.0, v138
	v_add_f32_e32 v139, 1.0, v139
	v_rcp_f32_e32 v130, v130
	v_rcp_f32_e32 v131, v131
	v_rcp_f32_e32 v132, v132
	v_rcp_f32_e32 v133, v133
	v_rcp_f32_e32 v136, v136
	v_rcp_f32_e32 v137, v137
	v_rcp_f32_e32 v138, v138
	v_rcp_f32_e32 v139, v139
	v_cvt_pk_bf16_f32 v130, v130, v131
	v_cvt_pk_bf16_f32 v131, v132, v133
	v_cvt_pk_bf16_f32 v132, v136, v137
	v_cvt_pk_bf16_f32 v133, v138, v139
	flat_store_dwordx4 v[134:135], v[130:133] offset:256 sc1
	v_mul_f32_e32 v136, 0xbfb8aa3b, v72
	v_mul_f32_e32 v137, 0xbfb8aa3b, v73
	v_mul_f32_e32 v132, 0xbfb8aa3b, v76
	v_mul_f32_e32 v133, 0xbfb8aa3b, v77
	v_exp_f32_e32 v132, v132
	v_exp_f32_e32 v133, v133
	v_or_b32_e32 v130, 48, v172
	v_mad_i64_i32 v[130:131], s[10:11], v130, s20, v[128:129]
	v_lshl_add_u64 v[130:131], v[130:131], 0, s[8:9]
	v_lshl_add_u64 v[134:135], v[130:131], 0, v[152:153]
	v_add_f32_e32 v130, 1.0, v132
	v_add_f32_e32 v131, 1.0, v133
	v_mul_f32_e32 v132, 0xbfb8aa3b, v78
	v_mul_f32_e32 v133, 0xbfb8aa3b, v79
	v_exp_f32_e32 v132, v132
	v_exp_f32_e32 v133, v133
	v_exp_f32_e32 v136, v136
	v_exp_f32_e32 v137, v137
	v_mul_f32_e32 v138, 0xbfb8aa3b, v74
	v_mul_f32_e32 v139, 0xbfb8aa3b, v75
	v_add_f32_e32 v132, 1.0, v132
	v_add_f32_e32 v133, 1.0, v133
	v_add_f32_e32 v136, 1.0, v136
	v_add_f32_e32 v137, 1.0, v137
	v_exp_f32_e32 v138, v138
	v_exp_f32_e32 v139, v139
	v_rcp_f32_e32 v130, v130
	v_rcp_f32_e32 v131, v131
	v_rcp_f32_e32 v132, v132
	v_rcp_f32_e32 v133, v133
	v_rcp_f32_e32 v136, v136
	v_rcp_f32_e32 v137, v137
	v_add_f32_e32 v138, 1.0, v138
	v_add_f32_e32 v139, 1.0, v139
	v_rcp_f32_e32 v138, v138
	v_rcp_f32_e32 v139, v139
	v_cvt_pk_bf16_f32 v130, v130, v131
	v_cvt_pk_bf16_f32 v131, v132, v133
	v_cvt_pk_bf16_f32 v132, v136, v137
	v_mul_f32_e32 v136, 0xbfb8aa3b, v68
	v_mul_f32_e32 v137, 0xbfb8aa3b, v69
	v_exp_f32_e32 v136, v136
	v_exp_f32_e32 v137, v137
	v_cvt_pk_bf16_f32 v133, v138, v139
	flat_store_dwordx4 v[134:135], v[130:133] sc1
	v_mul_f32_e32 v138, 0xbfb8aa3b, v66
	v_mul_f32_e32 v139, 0xbfb8aa3b, v67
	v_add_f32_e32 v130, 1.0, v136
	v_add_f32_e32 v131, 1.0, v137
	v_mul_f32_e32 v132, 0xbfb8aa3b, v70
	v_mul_f32_e32 v133, 0xbfb8aa3b, v71
	v_mul_f32_e32 v136, 0xbfb8aa3b, v64
	v_mul_f32_e32 v137, 0xbfb8aa3b, v65
	v_exp_f32_e32 v132, v132
	v_exp_f32_e32 v133, v133
	v_exp_f32_e32 v136, v136
	v_exp_f32_e32 v137, v137
	v_exp_f32_e32 v138, v138
	v_exp_f32_e32 v139, v139
	v_add_f32_e32 v132, 1.0, v132
	v_add_f32_e32 v133, 1.0, v133
	v_add_f32_e32 v136, 1.0, v136
	v_add_f32_e32 v137, 1.0, v137
	v_add_f32_e32 v138, 1.0, v138
	v_add_f32_e32 v139, 1.0, v139
	v_rcp_f32_e32 v130, v130
	v_rcp_f32_e32 v131, v131
	v_rcp_f32_e32 v132, v132
	v_rcp_f32_e32 v133, v133
	v_rcp_f32_e32 v136, v136
	v_rcp_f32_e32 v137, v137
	v_rcp_f32_e32 v138, v138
	v_rcp_f32_e32 v139, v139
	v_cvt_pk_bf16_f32 v130, v130, v131
	v_cvt_pk_bf16_f32 v131, v132, v133
	v_cvt_pk_bf16_f32 v132, v136, v137
	v_cvt_pk_bf16_f32 v133, v138, v139
	flat_store_dwordx4 v[134:135], v[130:133] offset:256 sc1
	v_mul_f32_e32 v136, 0xbfb8aa3b, v56
	v_mul_f32_e32 v137, 0xbfb8aa3b, v57
	v_mul_f32_e32 v132, 0xbfb8aa3b, v60
	v_mul_f32_e32 v133, 0xbfb8aa3b, v61
	v_exp_f32_e32 v132, v132
	v_exp_f32_e32 v133, v133
	v_add_u32_e32 v130, 0x80, v172
	v_mad_i64_i32 v[130:131], s[10:11], v130, s20, v[128:129]
	v_lshl_add_u64 v[130:131], v[130:131], 0, s[8:9]
	v_lshl_add_u64 v[134:135], v[130:131], 0, v[152:153]
	v_add_f32_e32 v130, 1.0, v132
	v_add_f32_e32 v131, 1.0, v133
	v_mul_f32_e32 v132, 0xbfb8aa3b, v62
	v_mul_f32_e32 v133, 0xbfb8aa3b, v63
	v_exp_f32_e32 v132, v132
	v_exp_f32_e32 v133, v133
	v_exp_f32_e32 v136, v136
	v_exp_f32_e32 v137, v137
	v_mul_f32_e32 v138, 0xbfb8aa3b, v58
	v_mul_f32_e32 v139, 0xbfb8aa3b, v59
	v_add_f32_e32 v132, 1.0, v132
	v_add_f32_e32 v133, 1.0, v133
	v_add_f32_e32 v136, 1.0, v136
	v_add_f32_e32 v137, 1.0, v137
	v_exp_f32_e32 v138, v138
	v_exp_f32_e32 v139, v139
	v_rcp_f32_e32 v130, v130
	v_rcp_f32_e32 v131, v131
	v_rcp_f32_e32 v132, v132
	v_rcp_f32_e32 v133, v133
	v_rcp_f32_e32 v136, v136
	v_rcp_f32_e32 v137, v137
	v_add_f32_e32 v138, 1.0, v138
	v_add_f32_e32 v139, 1.0, v139
	v_rcp_f32_e32 v138, v138
	v_rcp_f32_e32 v139, v139
	v_cvt_pk_bf16_f32 v130, v130, v131
	v_cvt_pk_bf16_f32 v131, v132, v133
	v_cvt_pk_bf16_f32 v132, v136, v137
	v_mul_f32_e32 v136, 0xbfb8aa3b, v52
	v_mul_f32_e32 v137, 0xbfb8aa3b, v53
	v_exp_f32_e32 v136, v136
	v_exp_f32_e32 v137, v137
	v_cvt_pk_bf16_f32 v133, v138, v139
	flat_store_dwordx4 v[134:135], v[130:133] sc1
	v_mul_f32_e32 v138, 0xbfb8aa3b, v50
	v_mul_f32_e32 v139, 0xbfb8aa3b, v51
	v_add_f32_e32 v130, 1.0, v136
	v_add_f32_e32 v131, 1.0, v137
	v_mul_f32_e32 v132, 0xbfb8aa3b, v54
	v_mul_f32_e32 v133, 0xbfb8aa3b, v55
	v_mul_f32_e32 v136, 0xbfb8aa3b, v48
	v_mul_f32_e32 v137, 0xbfb8aa3b, v49
	v_exp_f32_e32 v132, v132
	v_exp_f32_e32 v133, v133
	v_exp_f32_e32 v136, v136
	v_exp_f32_e32 v137, v137
	v_exp_f32_e32 v138, v138
	v_exp_f32_e32 v139, v139
	v_add_f32_e32 v132, 1.0, v132
	v_add_f32_e32 v133, 1.0, v133
	v_add_f32_e32 v136, 1.0, v136
	v_add_f32_e32 v137, 1.0, v137
	v_add_f32_e32 v138, 1.0, v138
	v_add_f32_e32 v139, 1.0, v139
	v_rcp_f32_e32 v130, v130
	v_rcp_f32_e32 v131, v131
	v_rcp_f32_e32 v132, v132
	v_rcp_f32_e32 v133, v133
	v_rcp_f32_e32 v136, v136
	v_rcp_f32_e32 v137, v137
	v_rcp_f32_e32 v138, v138
	v_rcp_f32_e32 v139, v139
	v_cvt_pk_bf16_f32 v130, v130, v131
	v_cvt_pk_bf16_f32 v131, v132, v133
	v_cvt_pk_bf16_f32 v132, v136, v137
	v_cvt_pk_bf16_f32 v133, v138, v139
	flat_store_dwordx4 v[134:135], v[130:133] offset:256 sc1
	v_mul_f32_e32 v136, 0xbfb8aa3b, v40
	v_mul_f32_e32 v137, 0xbfb8aa3b, v41
	v_mul_f32_e32 v132, 0xbfb8aa3b, v44
	v_mul_f32_e32 v133, 0xbfb8aa3b, v45
	v_exp_f32_e32 v132, v132
	v_exp_f32_e32 v133, v133
	v_add_u32_e32 v130, 0x90, v172
	v_mad_i64_i32 v[130:131], s[10:11], v130, s20, v[128:129]
	v_lshl_add_u64 v[130:131], v[130:131], 0, s[8:9]
	v_lshl_add_u64 v[134:135], v[130:131], 0, v[152:153]
	v_add_f32_e32 v130, 1.0, v132
	v_add_f32_e32 v131, 1.0, v133
	v_mul_f32_e32 v132, 0xbfb8aa3b, v46
	v_mul_f32_e32 v133, 0xbfb8aa3b, v47
	v_exp_f32_e32 v132, v132
	v_exp_f32_e32 v133, v133
	v_exp_f32_e32 v136, v136
	v_exp_f32_e32 v137, v137
	v_mul_f32_e32 v138, 0xbfb8aa3b, v42
	v_mul_f32_e32 v139, 0xbfb8aa3b, v43
	v_add_f32_e32 v132, 1.0, v132
	v_add_f32_e32 v133, 1.0, v133
	v_add_f32_e32 v136, 1.0, v136
	v_add_f32_e32 v137, 1.0, v137
	v_exp_f32_e32 v138, v138
	v_exp_f32_e32 v139, v139
	v_rcp_f32_e32 v130, v130
	v_rcp_f32_e32 v131, v131
	v_rcp_f32_e32 v132, v132
	v_rcp_f32_e32 v133, v133
	v_rcp_f32_e32 v136, v136
	v_rcp_f32_e32 v137, v137
	v_add_f32_e32 v138, 1.0, v138
	v_add_f32_e32 v139, 1.0, v139
	v_rcp_f32_e32 v138, v138
	v_rcp_f32_e32 v139, v139
	v_cvt_pk_bf16_f32 v130, v130, v131
	v_cvt_pk_bf16_f32 v131, v132, v133
	v_cvt_pk_bf16_f32 v132, v136, v137
	v_mul_f32_e32 v136, 0xbfb8aa3b, v36
	v_mul_f32_e32 v137, 0xbfb8aa3b, v37
	v_exp_f32_e32 v136, v136
	v_exp_f32_e32 v137, v137
	v_cvt_pk_bf16_f32 v133, v138, v139
	flat_store_dwordx4 v[134:135], v[130:133] sc1
	v_mul_f32_e32 v138, 0xbfb8aa3b, v34
	v_mul_f32_e32 v139, 0xbfb8aa3b, v35
	v_add_f32_e32 v130, 1.0, v136
	v_add_f32_e32 v131, 1.0, v137
	v_mul_f32_e32 v132, 0xbfb8aa3b, v38
	v_mul_f32_e32 v133, 0xbfb8aa3b, v39
	v_mul_f32_e32 v136, 0xbfb8aa3b, v32
	v_mul_f32_e32 v137, 0xbfb8aa3b, v33
	v_exp_f32_e32 v132, v132
	v_exp_f32_e32 v133, v133
	v_exp_f32_e32 v136, v136
	v_exp_f32_e32 v137, v137
	v_exp_f32_e32 v138, v138
	v_exp_f32_e32 v139, v139
	v_add_f32_e32 v132, 1.0, v132
	v_add_f32_e32 v133, 1.0, v133
	v_add_f32_e32 v136, 1.0, v136
	v_add_f32_e32 v137, 1.0, v137
	v_add_f32_e32 v138, 1.0, v138
	v_add_f32_e32 v139, 1.0, v139
	v_rcp_f32_e32 v130, v130
	v_rcp_f32_e32 v131, v131
	v_rcp_f32_e32 v132, v132
	v_rcp_f32_e32 v133, v133
	v_rcp_f32_e32 v136, v136
	v_rcp_f32_e32 v137, v137
	v_rcp_f32_e32 v138, v138
	v_rcp_f32_e32 v139, v139
	v_cvt_pk_bf16_f32 v130, v130, v131
	v_cvt_pk_bf16_f32 v131, v132, v133
	v_cvt_pk_bf16_f32 v132, v136, v137
	v_cvt_pk_bf16_f32 v133, v138, v139
	flat_store_dwordx4 v[134:135], v[130:133] offset:256 sc1
	v_mul_f32_e32 v136, 0xbfb8aa3b, v24
	v_mul_f32_e32 v137, 0xbfb8aa3b, v25
	v_mul_f32_e32 v132, 0xbfb8aa3b, v28
	v_mul_f32_e32 v133, 0xbfb8aa3b, v29
	v_exp_f32_e32 v132, v132
	v_exp_f32_e32 v133, v133
	v_add_u32_e32 v130, 0xa0, v172
	v_mad_i64_i32 v[130:131], s[10:11], v130, s20, v[128:129]
	v_lshl_add_u64 v[130:131], v[130:131], 0, s[8:9]
	v_lshl_add_u64 v[134:135], v[130:131], 0, v[152:153]
	v_add_f32_e32 v130, 1.0, v132
	v_add_f32_e32 v131, 1.0, v133
	v_mul_f32_e32 v132, 0xbfb8aa3b, v30
	v_mul_f32_e32 v133, 0xbfb8aa3b, v31
	v_exp_f32_e32 v132, v132
	v_exp_f32_e32 v133, v133
	v_exp_f32_e32 v136, v136
	v_exp_f32_e32 v137, v137
	v_mul_f32_e32 v138, 0xbfb8aa3b, v26
	v_mul_f32_e32 v139, 0xbfb8aa3b, v27
	v_add_f32_e32 v132, 1.0, v132
	v_add_f32_e32 v133, 1.0, v133
	v_add_f32_e32 v136, 1.0, v136
	v_add_f32_e32 v137, 1.0, v137
	v_exp_f32_e32 v138, v138
	v_exp_f32_e32 v139, v139
	v_rcp_f32_e32 v130, v130
	v_rcp_f32_e32 v131, v131
	v_rcp_f32_e32 v132, v132
	v_rcp_f32_e32 v133, v133
	v_rcp_f32_e32 v136, v136
	v_rcp_f32_e32 v137, v137
	v_add_f32_e32 v138, 1.0, v138
	v_add_f32_e32 v139, 1.0, v139
	v_rcp_f32_e32 v138, v138
	v_rcp_f32_e32 v139, v139
	v_cvt_pk_bf16_f32 v130, v130, v131
	v_cvt_pk_bf16_f32 v131, v132, v133
	v_cvt_pk_bf16_f32 v132, v136, v137
	v_mul_f32_e32 v136, 0xbfb8aa3b, v20
	v_mul_f32_e32 v137, 0xbfb8aa3b, v21
	v_exp_f32_e32 v136, v136
	v_exp_f32_e32 v137, v137
	v_cvt_pk_bf16_f32 v133, v138, v139
	flat_store_dwordx4 v[134:135], v[130:133] sc1
	v_mul_f32_e32 v138, 0xbfb8aa3b, v18
	v_mul_f32_e32 v139, 0xbfb8aa3b, v19
	v_add_f32_e32 v130, 1.0, v136
	v_add_f32_e32 v131, 1.0, v137
	v_mul_f32_e32 v132, 0xbfb8aa3b, v22
	v_mul_f32_e32 v133, 0xbfb8aa3b, v23
	v_mul_f32_e32 v136, 0xbfb8aa3b, v16
	v_mul_f32_e32 v137, 0xbfb8aa3b, v17
	v_exp_f32_e32 v132, v132
	v_exp_f32_e32 v133, v133
	v_exp_f32_e32 v136, v136
	v_exp_f32_e32 v137, v137
	v_exp_f32_e32 v138, v138
	v_exp_f32_e32 v139, v139
	v_add_f32_e32 v132, 1.0, v132
	v_add_f32_e32 v133, 1.0, v133
	v_add_f32_e32 v136, 1.0, v136
	v_add_f32_e32 v137, 1.0, v137
	v_add_f32_e32 v138, 1.0, v138
	v_add_f32_e32 v139, 1.0, v139
	v_rcp_f32_e32 v130, v130
	v_rcp_f32_e32 v131, v131
	v_rcp_f32_e32 v132, v132
	v_rcp_f32_e32 v133, v133
	v_rcp_f32_e32 v136, v136
	v_rcp_f32_e32 v137, v137
	v_rcp_f32_e32 v138, v138
	v_rcp_f32_e32 v139, v139
	v_cvt_pk_bf16_f32 v130, v130, v131
	v_cvt_pk_bf16_f32 v131, v132, v133
	v_cvt_pk_bf16_f32 v132, v136, v137
	v_cvt_pk_bf16_f32 v133, v138, v139
	flat_store_dwordx4 v[134:135], v[130:133] offset:256 sc1
	v_mul_f32_e32 v134, 0xbfb8aa3b, v8
	v_mul_f32_e32 v135, 0xbfb8aa3b, v9
	v_add_u32_e32 v130, 0xb0, v172
	v_mad_i64_i32 v[128:129], s[10:11], v130, s20, v[128:129]
	v_mul_f32_e32 v130, 0xbfb8aa3b, v12
	v_mul_f32_e32 v131, 0xbfb8aa3b, v13
	v_exp_f32_e32 v130, v130
	v_exp_f32_e32 v131, v131
	v_lshl_add_u64 v[128:129], v[128:129], 0, s[8:9]
	v_lshl_add_u64 v[132:133], v[128:129], 0, v[152:153]
	v_add_f32_e32 v128, 1.0, v130
	v_add_f32_e32 v129, 1.0, v131
	v_mul_f32_e32 v130, 0xbfb8aa3b, v14
	v_mul_f32_e32 v131, 0xbfb8aa3b, v15
	v_exp_f32_e32 v130, v130
	v_exp_f32_e32 v131, v131
	v_exp_f32_e32 v134, v134
	v_exp_f32_e32 v135, v135
	v_mul_f32_e32 v136, 0xbfb8aa3b, v10
	v_mul_f32_e32 v137, 0xbfb8aa3b, v11
	v_add_f32_e32 v130, 1.0, v130
	v_add_f32_e32 v131, 1.0, v131
	v_add_f32_e32 v134, 1.0, v134
	v_add_f32_e32 v135, 1.0, v135
	v_exp_f32_e32 v136, v136
	v_exp_f32_e32 v137, v137
	v_rcp_f32_e32 v128, v128
	v_rcp_f32_e32 v129, v129
	v_rcp_f32_e32 v130, v130
	v_rcp_f32_e32 v131, v131
	v_rcp_f32_e32 v134, v134
	v_rcp_f32_e32 v135, v135
	v_add_f32_e32 v136, 1.0, v136
	v_add_f32_e32 v137, 1.0, v137
	v_rcp_f32_e32 v136, v136
	v_rcp_f32_e32 v137, v137
	v_cvt_pk_bf16_f32 v128, v128, v129
	v_cvt_pk_bf16_f32 v129, v130, v131
	v_cvt_pk_bf16_f32 v130, v134, v135
	v_mul_f32_e32 v134, 0xbfb8aa3b, v4
	v_mul_f32_e32 v135, 0xbfb8aa3b, v5
	v_exp_f32_e32 v134, v134
	v_exp_f32_e32 v135, v135
	v_cvt_pk_bf16_f32 v131, v136, v137
	flat_store_dwordx4 v[132:133], v[128:131] sc1
	v_mul_f32_e32 v136, 0xbfb8aa3b, v2
	v_mul_f32_e32 v137, 0xbfb8aa3b, v3
	v_add_f32_e32 v128, 1.0, v134
	v_add_f32_e32 v129, 1.0, v135
	v_mul_f32_e32 v130, 0xbfb8aa3b, v6
	v_mul_f32_e32 v131, 0xbfb8aa3b, v7
	v_mul_f32_e32 v134, 0xbfb8aa3b, v0
	v_mul_f32_e32 v135, 0xbfb8aa3b, v1
	v_exp_f32_e32 v130, v130
	v_exp_f32_e32 v131, v131
	v_exp_f32_e32 v134, v134
	v_exp_f32_e32 v135, v135
	v_exp_f32_e32 v136, v136
	v_exp_f32_e32 v137, v137
	v_add_f32_e32 v130, 1.0, v130
	v_add_f32_e32 v131, 1.0, v131
	v_add_f32_e32 v134, 1.0, v134
	v_add_f32_e32 v135, 1.0, v135
	v_add_f32_e32 v136, 1.0, v136
	v_add_f32_e32 v137, 1.0, v137
	v_rcp_f32_e32 v128, v128
	v_rcp_f32_e32 v129, v129
	v_rcp_f32_e32 v130, v130
	v_rcp_f32_e32 v131, v131
	v_rcp_f32_e32 v134, v134
	v_rcp_f32_e32 v135, v135
	v_rcp_f32_e32 v136, v136
	v_rcp_f32_e32 v137, v137
	v_cvt_pk_bf16_f32 v128, v128, v129
	v_cvt_pk_bf16_f32 v129, v130, v131
	v_cvt_pk_bf16_f32 v130, v134, v135
	v_cvt_pk_bf16_f32 v131, v136, v137
	s_mov_b64 s[8:9], 0
	flat_store_dwordx4 v[132:133], v[128:131] offset:256 sc1

.LBB0_1019:
	s_or_saveexec_b64 s[8:9], s[8:9]
	s_ashr_i32 s2, s86, 7
	v_lshrrev_b32_e32 v128, 4, v191
	s_and_b32 s2, s2, -2
	v_readlane_b32 s10, v254, 22
	v_lshlrev_b32_e32 v129, 3, v128
	v_lshlrev_b32_e32 v128, 2, v128
	s_add_i32 s10, s2, s10
	v_and_b32_e32 v129, 16, v129
	v_and_b32_e32 v130, 4, v128
	s_ashr_i32 s11, s10, 31
	s_lshl_b64 s[10:11], s[10:11], 15
	v_lshlrev_b32_e32 v128, 2, v129
	v_lshlrev_b32_e32 v130, 2, v130
	s_xor_b64 exec, exec, s[8:9]
	s_cbranch_execz .LBB0_1021
	v_readlane_b32 s20, v254, 37
	v_readlane_b32 s21, v254, 38
	s_add_u32 s20, s20, s10
	v_lshlrev_b32_e32 v129, 7, v172
	s_addc_u32 s21, s21, s11
	v_and_b32_e32 v152, 0x6780, v129
	v_lshl_add_u64 v[134:135], s[20:21], 0, v[152:153]
	v_mov_b32_e32 v129, v153
	v_lshl_add_u64 v[134:135], v[134:135], 0, v[128:129]
	v_mov_b32_e32 v131, v153
	v_lshl_add_u64 v[134:135], v[134:135], 0, v[130:131]
	v_ashrrev_i32_e32 v173, 31, v172
	flat_store_dwordx4 v[134:135], v[124:127] sc1
	flat_store_dwordx4 v[134:135], v[120:123] offset:32 sc1
	v_mov_b64_e32 v[142:143], v[172:173]
	v_mov_b32_e32 v138, v120
	v_mov_b32_e32 v139, v121
	v_mov_b32_e32 v140, v122
	v_mov_b32_e32 v141, v123
	v_mov_b32_e32 v134, v124
	v_mov_b32_e32 v135, v125
	v_mov_b32_e32 v136, v126
	v_mov_b32_e32 v137, v127

.LBB0_1023:
	s_andn2_saveexec_b64 s[8:9], s[8:9]
	s_cbranch_execz .LBB0_1025
	v_readlane_b32 s20, v254, 37
	v_readlane_b32 s21, v254, 38
	s_add_u32 s20, s20, s10
	v_lshlrev_b32_e32 v129, 7, v134
	s_addc_u32 s21, s21, s11
	v_and_b32_e32 v136, 0x6f80, v129
	v_mov_b32_e32 v137, v153
	v_lshl_add_u64 v[136:137], s[20:21], 0, v[136:137]
	v_mov_b32_e32 v129, v153
	v_lshl_add_u64 v[136:137], v[136:137], 0, v[128:129]
	v_mov_b32_e32 v131, v153
	v_lshl_add_u64 v[136:137], v[136:137], 0, v[130:131]
	flat_store_dwordx4 v[136:137], v[108:111] sc1
	flat_store_dwordx4 v[136:137], v[104:107] offset:32 sc1
	v_ashrrev_i32_e32 v135, 31, v134
	v_mov_b32_e32 v140, v104
	v_mov_b32_e32 v141, v105
	v_mov_b32_e32 v142, v106
	v_mov_b32_e32 v143, v107
	v_mov_b32_e32 v136, v108
	v_mov_b32_e32 v137, v109
	v_mov_b32_e32 v138, v110
	v_mov_b32_e32 v139, v111

.LBB0_1027:
	s_andn2_saveexec_b64 s[8:9], s[8:9]
	s_cbranch_execz .LBB0_1029
	v_readlane_b32 s20, v254, 37
	v_readlane_b32 s21, v254, 38
	s_add_u32 s20, s20, s10
	v_lshlrev_b32_e32 v129, 7, v134
	s_addc_u32 s21, s21, s11
	v_and_b32_e32 v136, 0x7780, v129
	v_mov_b32_e32 v137, v153
	v_lshl_add_u64 v[136:137], s[20:21], 0, v[136:137]
	v_mov_b32_e32 v129, v153
	v_lshl_add_u64 v[136:137], v[136:137], 0, v[128:129]
	v_mov_b32_e32 v131, v153
	v_lshl_add_u64 v[136:137], v[136:137], 0, v[130:131]
	flat_store_dwordx4 v[136:137], v[92:95] sc1
	flat_store_dwordx4 v[136:137], v[88:91] offset:32 sc1
	v_ashrrev_i32_e32 v135, 31, v134
	v_mov_b32_e32 v140, v88
	v_mov_b32_e32 v141, v89
	v_mov_b32_e32 v142, v90
	v_mov_b32_e32 v143, v91
	v_mov_b32_e32 v136, v92
	v_mov_b32_e32 v137, v93
	v_mov_b32_e32 v138, v94
	v_mov_b32_e32 v139, v95

.LBB0_1031:
	s_andn2_saveexec_b64 s[8:9], s[8:9]
	s_cbranch_execz .LBB0_1033
	v_readlane_b32 s20, v254, 37
	v_readlane_b32 s21, v254, 38
	s_add_u32 s10, s20, s10
	v_lshlrev_b32_e32 v129, 7, v134
	s_addc_u32 s11, s21, s11
	v_and_b32_e32 v132, 0x7f80, v129
	v_mov_b32_e32 v133, v153
	v_lshl_add_u64 v[132:133], s[10:11], 0, v[132:133]
	v_mov_b32_e32 v129, v153
	v_lshl_add_u64 v[132:133], v[132:133], 0, v[128:129]
	v_mov_b32_e32 v131, v153
	v_lshl_add_u64 v[132:133], v[132:133], 0, v[130:131]
	v_ashrrev_i32_e32 v135, 31, v134
	v_mov_b32_e32 v140, v72
	v_mov_b32_e32 v141, v73
	v_mov_b32_e32 v142, v74
	v_mov_b32_e32 v143, v75
	v_mov_b32_e32 v136, v76
	v_mov_b32_e32 v137, v77
	v_mov_b32_e32 v138, v78
	v_mov_b32_e32 v139, v79
	flat_store_dwordx4 v[132:133], v[76:79] sc1
	flat_store_dwordx4 v[132:133], v[72:75] offset:32 sc1

.LBB0_1035:
	s_or_saveexec_b64 s[8:9], s[8:9]
	v_ashrrev_i32_e32 v129, 7, v136
	v_and_b32_e32 v129, -2, v129
	v_readlane_b32 s2, v254, 22
	v_readlane_b32 s10, v254, 37
	v_readlane_b32 s11, v254, 38
	v_add_u32_e32 v134, s2, v129
	v_ashrrev_i32_e32 v135, 31, v134
	v_lshlrev_b64 v[134:135], 15, v[134:135]
	v_lshl_add_u64 v[134:135], s[10:11], 0, v[134:135]
	s_xor_b64 exec, exec, s[8:9]
	s_cbranch_execz .LBB0_1037
	v_lshlrev_b32_e32 v129, 7, v136
	v_and_b32_e32 v138, 0x6780, v129
	v_mov_b32_e32 v139, v153
	v_lshl_add_u64 v[138:139], v[134:135], 0, v[138:139]
	v_mov_b32_e32 v129, v153
	v_lshl_add_u64 v[138:139], v[138:139], 0, v[128:129]
	v_mov_b32_e32 v131, v153
	v_lshl_add_u64 v[138:139], v[138:139], 0, v[130:131]
	v_ashrrev_i32_e32 v137, 31, v136
	flat_store_dwordx4 v[138:139], v[60:63] sc1
	flat_store_dwordx4 v[138:139], v[56:59] offset:32 sc1
	v_mov_b64_e32 v[146:147], v[136:137]
	v_mov_b32_e32 v142, v56
	v_mov_b32_e32 v143, v57
	v_mov_b32_e32 v144, v58
	v_mov_b32_e32 v145, v59
	v_mov_b32_e32 v138, v60
	v_mov_b32_e32 v139, v61
	v_mov_b32_e32 v140, v62
	v_mov_b32_e32 v141, v63

.LBB0_1039:
	s_andn2_saveexec_b64 s[8:9], s[8:9]
	s_cbranch_execz .LBB0_1041
	v_lshlrev_b32_e32 v129, 7, v136
	v_and_b32_e32 v138, 0x6f80, v129
	v_mov_b32_e32 v139, v153
	v_lshl_add_u64 v[138:139], v[134:135], 0, v[138:139]
	v_mov_b32_e32 v129, v153
	v_lshl_add_u64 v[138:139], v[138:139], 0, v[128:129]
	v_mov_b32_e32 v131, v153
	v_lshl_add_u64 v[138:139], v[138:139], 0, v[130:131]
	flat_store_dwordx4 v[138:139], v[44:47] sc1
	flat_store_dwordx4 v[138:139], v[40:43] offset:32 sc1
	v_ashrrev_i32_e32 v137, 31, v136
	v_mov_b32_e32 v142, v40
	v_mov_b32_e32 v143, v41
	v_mov_b32_e32 v144, v42
	v_mov_b32_e32 v145, v43
	v_mov_b32_e32 v138, v44
	v_mov_b32_e32 v139, v45
	v_mov_b32_e32 v140, v46
	v_mov_b32_e32 v141, v47

.LBB0_1043:
	s_andn2_saveexec_b64 s[8:9], s[8:9]
	s_cbranch_execz .LBB0_1045
	v_lshlrev_b32_e32 v129, 7, v136
	v_and_b32_e32 v138, 0x7780, v129
	v_mov_b32_e32 v139, v153
	v_lshl_add_u64 v[138:139], v[134:135], 0, v[138:139]
	v_mov_b32_e32 v129, v153
	v_lshl_add_u64 v[138:139], v[138:139], 0, v[128:129]
	v_mov_b32_e32 v131, v153
	v_lshl_add_u64 v[138:139], v[138:139], 0, v[130:131]
	flat_store_dwordx4 v[138:139], v[28:31] sc1
	flat_store_dwordx4 v[138:139], v[24:27] offset:32 sc1
	v_ashrrev_i32_e32 v137, 31, v136
	v_mov_b32_e32 v142, v24
	v_mov_b32_e32 v143, v25
	v_mov_b32_e32 v144, v26
	v_mov_b32_e32 v145, v27
	v_mov_b32_e32 v138, v28
	v_mov_b32_e32 v139, v29
	v_mov_b32_e32 v140, v30
	v_mov_b32_e32 v141, v31

.LBB0_1047:
	s_andn2_saveexec_b64 s[8:9], s[8:9]
	s_cbranch_execz .LBB0_1049
	v_lshlrev_b32_e32 v129, 7, v136
	v_and_b32_e32 v132, 0x7f80, v129
	v_mov_b32_e32 v133, v153
	v_lshl_add_u64 v[132:133], v[134:135], 0, v[132:133]
	v_mov_b32_e32 v129, v153
	v_lshl_add_u64 v[128:129], v[132:133], 0, v[128:129]
	v_mov_b32_e32 v131, v153
	v_lshl_add_u64 v[128:129], v[128:129], 0, v[130:131]
	v_ashrrev_i32_e32 v137, 31, v136
	v_mov_b32_e32 v142, v8
	v_mov_b32_e32 v143, v9
	v_mov_b32_e32 v144, v10
	v_mov_b32_e32 v145, v11
	v_mov_b32_e32 v138, v12
	v_mov_b32_e32 v139, v13
	v_mov_b32_e32 v140, v14
	v_mov_b32_e32 v141, v15
	flat_store_dwordx4 v[128:129], v[12:15] sc1
	flat_store_dwordx4 v[128:129], v[8:11] offset:32 sc1

.LBB0_1058:
	s_or_b64 exec, exec, s[22:23]
	s_ashr_i32 s22, s86, 7
	s_and_b32 s22, s22, -2
	v_readlane_b32 s23, v254, 22
	s_add_i32 s22, s22, s23
	s_ashr_i32 s23, s22, 31
	v_cmp_gt_i32_e32 vcc, s43, v172
	s_lshl_b32 s26, s26, 8
	s_lshl_b64 s[24:25], s[22:23], 18
	s_and_b64 s[36:37], s[20:21], vcc
	v_lshlrev_b32_e32 v128, 2, v187
	s_and_saveexec_b64 s[22:23], s[36:37]
	s_cbranch_execz .LBB0_1060
	s_add_u32 s36, s40, s24
	v_lshlrev_b32_e32 v129, 10, v172
	s_addc_u32 s37, s41, s25
	v_and_b32_e32 v130, 0x33c00, v129
	s_waitcnt lgkmcnt(0)
	v_mov_b32_e32 v131, v153
	v_lshl_add_u64 v[130:131], s[36:37], 0, v[130:131]
	v_mov_b32_e32 v129, v153
	v_lshl_add_u64 v[130:131], v[130:131], 0, v[128:129]
	flat_store_dwordx4 v[130:131], v[124:127] sc1
	flat_store_dwordx4 v[130:131], v[120:123] offset:64 sc1
	flat_store_dwordx4 v[130:131], v[116:119] offset:512 sc1
	flat_store_dwordx4 v[130:131], v[112:115] offset:576 sc1

.LBB0_1066:
	s_or_b64 exec, exec, s[26:27]
	v_cmp_gt_i32_e32 vcc, s43, v130
	s_and_b64 s[36:37], s[20:21], vcc
	s_and_saveexec_b64 s[26:27], s[36:37]
	s_cbranch_execz .LBB0_1068
	s_add_u32 s36, s40, s24
	v_lshlrev_b32_e32 v129, 10, v130
	s_addc_u32 s37, s41, s25
	v_and_b32_e32 v130, 0x37c00, v129
	v_mov_b32_e32 v131, v153
	v_lshl_add_u64 v[130:131], s[36:37], 0, v[130:131]
	v_mov_b32_e32 v129, v153
	v_lshl_add_u64 v[130:131], v[130:131], 0, v[128:129]
	flat_store_dwordx4 v[130:131], v[108:111] sc1
	flat_store_dwordx4 v[130:131], v[104:107] offset:64 sc1
	flat_store_dwordx4 v[130:131], v[100:103] offset:512 sc1
	flat_store_dwordx4 v[130:131], v[96:99] offset:576 sc1

.LBB0_1074:
	s_or_b64 exec, exec, s[26:27]
	v_cmp_gt_i32_e32 vcc, s43, v130
	s_and_b64 s[36:37], s[20:21], vcc
	s_and_saveexec_b64 s[26:27], s[36:37]
	s_cbranch_execz .LBB0_1076
	s_add_u32 s36, s40, s24
	v_lshlrev_b32_e32 v129, 10, v130
	s_addc_u32 s37, s41, s25
	v_and_b32_e32 v130, 0x3bc00, v129
	v_mov_b32_e32 v131, v153
	v_lshl_add_u64 v[130:131], s[36:37], 0, v[130:131]
	v_mov_b32_e32 v129, v153
	v_lshl_add_u64 v[130:131], v[130:131], 0, v[128:129]
	flat_store_dwordx4 v[130:131], v[92:95] sc1
	flat_store_dwordx4 v[130:131], v[88:91] offset:64 sc1
	flat_store_dwordx4 v[130:131], v[84:87] offset:512 sc1
	flat_store_dwordx4 v[130:131], v[80:83] offset:576 sc1

.LBB0_1082:
	s_or_b64 exec, exec, s[26:27]
	v_cmp_gt_i32_e32 vcc, s43, v130
	s_and_b64 s[36:37], s[20:21], vcc
	s_and_saveexec_b64 s[26:27], s[36:37]
	s_cbranch_execz .LBB0_1084
	s_add_u32 s24, s40, s24
	v_lshlrev_b32_e32 v129, 10, v130
	s_addc_u32 s25, s41, s25
	v_and_b32_e32 v130, 0x3fc00, v129
	v_mov_b32_e32 v131, v153
	v_lshl_add_u64 v[130:131], s[24:25], 0, v[130:131]
	v_mov_b32_e32 v129, v153
	v_lshl_add_u64 v[130:131], v[130:131], 0, v[128:129]
	flat_store_dwordx4 v[130:131], v[76:79] sc1
	flat_store_dwordx4 v[130:131], v[72:75] offset:64 sc1
	flat_store_dwordx4 v[130:131], v[68:71] offset:512 sc1
	flat_store_dwordx4 v[130:131], v[64:67] offset:576 sc1

.LBB0_1090:
	s_or_b64 exec, exec, s[24:25]
	v_ashrrev_i32_e32 v129, 7, v132
	v_and_b32_e32 v129, -2, v129
	v_readlane_b32 s23, v254, 22
	s_nop 1
	v_add_u32_e32 v130, s23, v129
	v_ashrrev_i32_e32 v131, 31, v130
	s_movk_i32 s23, 0xf80
	v_lshlrev_b64 v[130:131], 18, v[130:131]
	v_cmp_gt_i32_e32 vcc, s23, v172
	s_and_b64 s[26:27], s[20:21], vcc
	v_lshl_add_u64 v[130:131], s[40:41], 0, v[130:131]
	s_and_saveexec_b64 s[24:25], s[26:27]
	s_cbranch_execz .LBB0_1092
	v_lshlrev_b32_e32 v129, 10, v132
	v_and_b32_e32 v132, 0x33c00, v129
	v_mov_b32_e32 v133, v153
	v_lshl_add_u64 v[132:133], v[130:131], 0, v[132:133]
	v_mov_b32_e32 v129, v153
	v_lshl_add_u64 v[132:133], v[132:133], 0, v[128:129]
	flat_store_dwordx4 v[132:133], v[60:63] sc1
	flat_store_dwordx4 v[132:133], v[56:59] offset:64 sc1
	flat_store_dwordx4 v[132:133], v[52:55] offset:512 sc1
	flat_store_dwordx4 v[132:133], v[48:51] offset:576 sc1

.LBB0_1098:
	s_or_b64 exec, exec, s[24:25]
	s_movk_i32 s23, 0xf70
	v_cmp_gt_i32_e32 vcc, s23, v172
	s_and_b64 s[26:27], s[20:21], vcc
	s_and_saveexec_b64 s[24:25], s[26:27]
	s_cbranch_execz .LBB0_1100
	v_lshlrev_b32_e32 v129, 10, v132
	v_and_b32_e32 v132, 0x37c00, v129
	v_mov_b32_e32 v133, v153
	v_lshl_add_u64 v[132:133], v[130:131], 0, v[132:133]
	v_mov_b32_e32 v129, v153
	v_lshl_add_u64 v[132:133], v[132:133], 0, v[128:129]
	flat_store_dwordx4 v[132:133], v[44:47] sc1
	flat_store_dwordx4 v[132:133], v[40:43] offset:64 sc1
	flat_store_dwordx4 v[132:133], v[36:39] offset:512 sc1
	flat_store_dwordx4 v[132:133], v[32:35] offset:576 sc1

.LBB0_1106:
	s_or_b64 exec, exec, s[24:25]
	s_movk_i32 s23, 0xf60
	v_cmp_gt_i32_e32 vcc, s23, v172
	s_and_b64 s[26:27], s[20:21], vcc
	s_and_saveexec_b64 s[24:25], s[26:27]
	s_cbranch_execz .LBB0_1108
	v_lshlrev_b32_e32 v129, 10, v132
	v_and_b32_e32 v132, 0x3bc00, v129
	v_mov_b32_e32 v133, v153
	v_lshl_add_u64 v[132:133], v[130:131], 0, v[132:133]
	v_mov_b32_e32 v129, v153
	v_lshl_add_u64 v[132:133], v[132:133], 0, v[128:129]
	flat_store_dwordx4 v[132:133], v[28:31] sc1
	flat_store_dwordx4 v[132:133], v[24:27] offset:64 sc1
	flat_store_dwordx4 v[132:133], v[20:23] offset:512 sc1
	flat_store_dwordx4 v[132:133], v[16:19] offset:576 sc1

.LBB0_1114:
	s_or_b64 exec, exec, s[22:23]
	s_movk_i32 s2, 0xf50
	v_cmp_gt_i32_e32 vcc, s2, v172
	s_and_b64 s[10:11], s[20:21], vcc
	s_and_saveexec_b64 s[8:9], s[10:11]
	s_cbranch_execz .LBB0_1116
	v_lshlrev_b32_e32 v129, 10, v132
	v_and_b32_e32 v152, 0x3fc00, v129
	v_lshl_add_u64 v[130:131], v[130:131], 0, v[152:153]
	v_mov_b32_e32 v129, v153
	v_lshl_add_u64 v[128:129], v[130:131], 0, v[128:129]
	flat_store_dwordx4 v[128:129], v[12:15] sc1
	flat_store_dwordx4 v[128:129], v[8:11] offset:64 sc1
	flat_store_dwordx4 v[128:129], v[4:7] offset:512 sc1
	flat_store_dwordx4 v[128:129], v[0:3] offset:576 sc1

.LBB0_1118:
	s_andn2_b64 vcc, exec, s[8:9]
	s_cbranch_vccnz .LBB0_1120
	v_mul_f32_e32 v130, 0xbfb8aa3b, v124
	v_mul_f32_e32 v131, 0xbfb8aa3b, v125
	v_mul_f32_e32 v132, 0xbfb8aa3b, v126
	v_mul_f32_e32 v133, 0xbfb8aa3b, v127
	v_mul_f32_e32 v138, 0xbfb8aa3b, v122
	v_mul_f32_e32 v139, 0xbfb8aa3b, v123
	v_exp_f32_e32 v130, v130
	v_exp_f32_e32 v131, v131
	v_exp_f32_e32 v132, v132
	v_exp_f32_e32 v133, v133
	v_exp_f32_e32 v138, v138
	v_exp_f32_e32 v139, v139
	s_waitcnt lgkmcnt(0)
	v_mul_f32_e32 v136, 0xbfb8aa3b, v120
	v_mul_f32_e32 v137, 0xbfb8aa3b, v121
	v_exp_f32_e32 v136, v136
	v_exp_f32_e32 v137, v137
	v_add_f32_e32 v130, 1.0, v130
	v_add_f32_e32 v131, 1.0, v131
	v_add_f32_e32 v132, 1.0, v132
	v_add_f32_e32 v133, 1.0, v133
	v_add_f32_e32 v138, 1.0, v138
	v_add_f32_e32 v139, 1.0, v139
	v_rcp_f32_e32 v130, v130
	v_rcp_f32_e32 v131, v131
	v_rcp_f32_e32 v132, v132
	v_rcp_f32_e32 v133, v133
	v_rcp_f32_e32 v138, v138
	v_rcp_f32_e32 v139, v139
	v_add_f32_e32 v136, 1.0, v136
	v_add_f32_e32 v137, 1.0, v137
	v_ashrrev_i32_e32 v173, 31, v172
	v_rcp_f32_e32 v136, v136
	v_rcp_f32_e32 v137, v137
	v_lshlrev_b64 v[128:129], 11, v[172:173]
	v_pk_mul_f32 v[130:131], v[124:125], v[130:131]
	v_pk_mul_f32 v[132:133], v[126:127], v[132:133]
	v_pk_mul_f32 v[138:139], v[122:123], v[138:139]
	v_lshl_add_u64 v[128:129], s[18:19], 0, v[128:129]
	s_lshl_b32 s2, s14, 9
	v_cvt_pk_bf16_f32 v130, v130, v131
	v_cvt_pk_bf16_f32 v131, v132, v133
	v_cvt_pk_bf16_f32 v133, v138, v139
	v_mul_f32_e32 v138, 0xbfb8aa3b, v116
	v_mul_f32_e32 v139, 0xbfb8aa3b, v117
	v_lshl_add_u64 v[128:129], v[128:129], 0, s[2:3]
	v_lshlrev_b32_e32 v152, 1, v186
	v_exp_f32_e32 v138, v138
	v_exp_f32_e32 v139, v139
	v_lshl_add_u64 v[128:129], v[128:129], 0, v[152:153]
	v_pk_mul_f32 v[136:137], v[120:121], v[136:137]
	s_mov_b32 s8, 0xeefe000
	v_cvt_pk_bf16_f32 v132, v136, v137
	v_add_co_u32_e32 v136, vcc, s8, v128
	s_mov_b64 s[10:11], 0xeefe800
	s_nop 0
	v_addc_co_u32_e32 v137, vcc, 0, v129, vcc
	flat_store_dwordx4 v[136:137], v[130:133] offset:2048 sc1
	v_mul_f32_e32 v136, 0xbfb8aa3b, v112
	v_mul_f32_e32 v137, 0xbfb8aa3b, v113
	v_add_f32_e32 v130, 1.0, v138
	v_add_f32_e32 v131, 1.0, v139
	v_mul_f32_e32 v132, 0xbfb8aa3b, v118
	v_mul_f32_e32 v133, 0xbfb8aa3b, v119
	v_mul_f32_e32 v138, 0xbfb8aa3b, v114
	v_mul_f32_e32 v139, 0xbfb8aa3b, v115
	v_exp_f32_e32 v132, v132
	v_exp_f32_e32 v133, v133
	v_exp_f32_e32 v136, v136
	v_exp_f32_e32 v137, v137
	v_exp_f32_e32 v138, v138
	v_exp_f32_e32 v139, v139
	v_add_f32_e32 v132, 1.0, v132
	v_add_f32_e32 v133, 1.0, v133
	v_add_f32_e32 v136, 1.0, v136
	v_add_f32_e32 v137, 1.0, v137
	v_add_f32_e32 v138, 1.0, v138
	v_add_f32_e32 v139, 1.0, v139
	v_rcp_f32_e32 v130, v130
	v_rcp_f32_e32 v131, v131
	v_rcp_f32_e32 v132, v132
	v_rcp_f32_e32 v133, v133
	v_rcp_f32_e32 v136, v136
	v_rcp_f32_e32 v137, v137
	v_rcp_f32_e32 v138, v138
	v_rcp_f32_e32 v139, v139
	v_pk_mul_f32 v[130:131], v[116:117], v[130:131]
	v_pk_mul_f32 v[132:133], v[118:119], v[132:133]
	v_pk_mul_f32 v[136:137], v[112:113], v[136:137]
	v_pk_mul_f32 v[138:139], v[114:115], v[138:139]
	v_lshl_add_u64 v[134:135], v[128:129], 0, s[10:11]
	v_cvt_pk_bf16_f32 v130, v130, v131
	v_cvt_pk_bf16_f32 v131, v132, v133
	v_cvt_pk_bf16_f32 v132, v136, v137
	v_cvt_pk_bf16_f32 v133, v138, v139
	flat_store_dwordx4 v[134:135], v[130:133] offset:256 sc1
	v_mul_f32_e32 v138, 0xbfb8aa3b, v104
	v_mul_f32_e32 v139, 0xbfb8aa3b, v105
	v_or_b32_e32 v130, 16, v172
	v_ashrrev_i32_e32 v131, 31, v130
	v_lshlrev_b64 v[130:131], 11, v[130:131]
	v_lshl_add_u64 v[130:131], s[18:19], 0, v[130:131]
	v_lshl_add_u64 v[130:131], v[130:131], 0, s[2:3]
	v_lshl_add_u64 v[134:135], v[130:131], 0, v[152:153]
	v_mul_f32_e32 v130, 0xbfb8aa3b, v108
	v_mul_f32_e32 v131, 0xbfb8aa3b, v109
	v_mul_f32_e32 v132, 0xbfb8aa3b, v110
	v_mul_f32_e32 v133, 0xbfb8aa3b, v111
	v_exp_f32_e32 v130, v130
	v_exp_f32_e32 v131, v131
	v_exp_f32_e32 v132, v132
	v_exp_f32_e32 v133, v133
	v_exp_f32_e32 v138, v138
	v_exp_f32_e32 v139, v139
	v_mul_f32_e32 v140, 0xbfb8aa3b, v106
	v_mul_f32_e32 v141, 0xbfb8aa3b, v107
	v_add_f32_e32 v130, 1.0, v130
	v_add_f32_e32 v131, 1.0, v131
	v_add_f32_e32 v132, 1.0, v132
	v_add_f32_e32 v133, 1.0, v133
	v_add_f32_e32 v138, 1.0, v138
	v_add_f32_e32 v139, 1.0, v139
	v_exp_f32_e32 v140, v140
	v_exp_f32_e32 v141, v141
	v_rcp_f32_e32 v130, v130
	v_rcp_f32_e32 v131, v131
	v_rcp_f32_e32 v132, v132
	v_rcp_f32_e32 v133, v133
	v_rcp_f32_e32 v138, v138
	v_rcp_f32_e32 v139, v139
	v_add_f32_e32 v140, 1.0, v140
	v_add_f32_e32 v141, 1.0, v141
	v_rcp_f32_e32 v140, v140
	v_rcp_f32_e32 v141, v141
	v_pk_mul_f32 v[130:131], v[108:109], v[130:131]
	v_pk_mul_f32 v[132:133], v[110:111], v[132:133]
	v_pk_mul_f32 v[138:139], v[104:105], v[138:139]
	v_cvt_pk_bf16_f32 v130, v130, v131
	v_cvt_pk_bf16_f32 v131, v132, v133
	v_cvt_pk_bf16_f32 v132, v138, v139
	v_mul_f32_e32 v138, 0xbfb8aa3b, v100
	v_mul_f32_e32 v139, 0xbfb8aa3b, v101
	v_exp_f32_e32 v138, v138
	v_exp_f32_e32 v139, v139
	v_lshl_add_u64 v[136:137], v[134:135], 0, s[10:11]
	v_pk_mul_f32 v[140:141], v[106:107], v[140:141]
	v_add_co_u32_e32 v134, vcc, s8, v134
	v_cvt_pk_bf16_f32 v133, v140, v141
	s_nop 0
	v_addc_co_u32_e32 v135, vcc, 0, v135, vcc
	flat_store_dwordx4 v[134:135], v[130:133] offset:2048 sc1
	v_mul_f32_e32 v134, 0xbfb8aa3b, v96
	v_mul_f32_e32 v135, 0xbfb8aa3b, v97
	v_add_f32_e32 v130, 1.0, v138
	v_add_f32_e32 v131, 1.0, v139
	v_mul_f32_e32 v132, 0xbfb8aa3b, v102
	v_mul_f32_e32 v133, 0xbfb8aa3b, v103
	v_mul_f32_e32 v138, 0xbfb8aa3b, v98
	v_mul_f32_e32 v139, 0xbfb8aa3b, v99
	v_exp_f32_e32 v132, v132
	v_exp_f32_e32 v133, v133
	v_exp_f32_e32 v134, v134
	v_exp_f32_e32 v135, v135
	v_exp_f32_e32 v138, v138
	v_exp_f32_e32 v139, v139
	v_add_f32_e32 v132, 1.0, v132
	v_add_f32_e32 v133, 1.0, v133
	v_add_f32_e32 v134, 1.0, v134
	v_add_f32_e32 v135, 1.0, v135
	v_add_f32_e32 v138, 1.0, v138
	v_add_f32_e32 v139, 1.0, v139
	v_rcp_f32_e32 v130, v130
	v_rcp_f32_e32 v131, v131
	v_rcp_f32_e32 v132, v132
	v_rcp_f32_e32 v133, v133
	v_rcp_f32_e32 v134, v134
	v_rcp_f32_e32 v135, v135
	v_rcp_f32_e32 v138, v138
	v_rcp_f32_e32 v139, v139
	v_pk_mul_f32 v[130:131], v[100:101], v[130:131]
	v_pk_mul_f32 v[132:133], v[102:103], v[132:133]
	v_pk_mul_f32 v[134:135], v[96:97], v[134:135]
	v_pk_mul_f32 v[138:139], v[98:99], v[138:139]
	v_cvt_pk_bf16_f32 v130, v130, v131
	v_cvt_pk_bf16_f32 v131, v132, v133
	v_cvt_pk_bf16_f32 v132, v134, v135
	v_cvt_pk_bf16_f32 v133, v138, v139
	flat_store_dwordx4 v[136:137], v[130:133] offset:256 sc1
	v_mul_f32_e32 v138, 0xbfb8aa3b, v88
	v_mul_f32_e32 v139, 0xbfb8aa3b, v89
	v_or_b32_e32 v130, 32, v172
	v_ashrrev_i32_e32 v131, 31, v130
	v_lshlrev_b64 v[130:131], 11, v[130:131]
	v_lshl_add_u64 v[130:131], s[18:19], 0, v[130:131]
	v_lshl_add_u64 v[130:131], v[130:131], 0, s[2:3]
	v_lshl_add_u64 v[134:135], v[130:131], 0, v[152:153]
	v_mul_f32_e32 v130, 0xbfb8aa3b, v92
	v_mul_f32_e32 v131, 0xbfb8aa3b, v93
	v_mul_f32_e32 v132, 0xbfb8aa3b, v94
	v_mul_f32_e32 v133, 0xbfb8aa3b, v95
	v_exp_f32_e32 v130, v130
	v_exp_f32_e32 v131, v131
	v_exp_f32_e32 v132, v132
	v_exp_f32_e32 v133, v133
	v_exp_f32_e32 v138, v138
	v_exp_f32_e32 v139, v139
	v_mul_f32_e32 v140, 0xbfb8aa3b, v90
	v_mul_f32_e32 v141, 0xbfb8aa3b, v91
	v_add_f32_e32 v130, 1.0, v130
	v_add_f32_e32 v131, 1.0, v131
	v_add_f32_e32 v132, 1.0, v132
	v_add_f32_e32 v133, 1.0, v133
	v_add_f32_e32 v138, 1.0, v138
	v_add_f32_e32 v139, 1.0, v139
	v_exp_f32_e32 v140, v140
	v_exp_f32_e32 v141, v141
	v_rcp_f32_e32 v130, v130
	v_rcp_f32_e32 v131, v131
	v_rcp_f32_e32 v132, v132
	v_rcp_f32_e32 v133, v133
	v_rcp_f32_e32 v138, v138
	v_rcp_f32_e32 v139, v139
	v_add_f32_e32 v140, 1.0, v140
	v_add_f32_e32 v141, 1.0, v141
	v_rcp_f32_e32 v140, v140
	v_rcp_f32_e32 v141, v141
	v_pk_mul_f32 v[130:131], v[92:93], v[130:131]
	v_pk_mul_f32 v[132:133], v[94:95], v[132:133]
	v_pk_mul_f32 v[138:139], v[88:89], v[138:139]
	v_cvt_pk_bf16_f32 v130, v130, v131
	v_cvt_pk_bf16_f32 v131, v132, v133
	v_cvt_pk_bf16_f32 v132, v138, v139
	v_mul_f32_e32 v138, 0xbfb8aa3b, v84
	v_mul_f32_e32 v139, 0xbfb8aa3b, v85
	v_exp_f32_e32 v138, v138
	v_exp_f32_e32 v139, v139
	v_lshl_add_u64 v[136:137], v[134:135], 0, s[10:11]
	v_pk_mul_f32 v[140:141], v[90:91], v[140:141]
	v_add_co_u32_e32 v134, vcc, s8, v134
	v_cvt_pk_bf16_f32 v133, v140, v141
	s_nop 0
	v_addc_co_u32_e32 v135, vcc, 0, v135, vcc
	flat_store_dwordx4 v[134:135], v[130:133] offset:2048 sc1
	v_mul_f32_e32 v134, 0xbfb8aa3b, v80
	v_mul_f32_e32 v135, 0xbfb8aa3b, v81
	v_add_f32_e32 v130, 1.0, v138
	v_add_f32_e32 v131, 1.0, v139
	v_mul_f32_e32 v132, 0xbfb8aa3b, v86
	v_mul_f32_e32 v133, 0xbfb8aa3b, v87
	v_mul_f32_e32 v138, 0xbfb8aa3b, v82
	v_mul_f32_e32 v139, 0xbfb8aa3b, v83
	v_exp_f32_e32 v132, v132
	v_exp_f32_e32 v133, v133
	v_exp_f32_e32 v134, v134
	v_exp_f32_e32 v135, v135
	v_exp_f32_e32 v138, v138
	v_exp_f32_e32 v139, v139
	v_add_f32_e32 v132, 1.0, v132
	v_add_f32_e32 v133, 1.0, v133
	v_add_f32_e32 v134, 1.0, v134
	v_add_f32_e32 v135, 1.0, v135
	v_add_f32_e32 v138, 1.0, v138
	v_add_f32_e32 v139, 1.0, v139
	v_rcp_f32_e32 v130, v130
	v_rcp_f32_e32 v131, v131
	v_rcp_f32_e32 v132, v132
	v_rcp_f32_e32 v133, v133
	v_rcp_f32_e32 v134, v134
	v_rcp_f32_e32 v135, v135
	v_rcp_f32_e32 v138, v138
	v_rcp_f32_e32 v139, v139
	v_pk_mul_f32 v[130:131], v[84:85], v[130:131]
	v_pk_mul_f32 v[132:133], v[86:87], v[132:133]
	v_pk_mul_f32 v[134:135], v[80:81], v[134:135]
	v_pk_mul_f32 v[138:139], v[82:83], v[138:139]
	v_cvt_pk_bf16_f32 v130, v130, v131
	v_cvt_pk_bf16_f32 v131, v132, v133
	v_cvt_pk_bf16_f32 v132, v134, v135
	v_cvt_pk_bf16_f32 v133, v138, v139
	flat_store_dwordx4 v[136:137], v[130:133] offset:256 sc1
	v_mul_f32_e32 v138, 0xbfb8aa3b, v72
	v_mul_f32_e32 v139, 0xbfb8aa3b, v73
	v_or_b32_e32 v130, 48, v172
	v_ashrrev_i32_e32 v131, 31, v130
	v_lshlrev_b64 v[130:131], 11, v[130:131]
	v_lshl_add_u64 v[130:131], s[18:19], 0, v[130:131]
	v_lshl_add_u64 v[130:131], v[130:131], 0, s[2:3]
	v_lshl_add_u64 v[134:135], v[130:131], 0, v[152:153]
	v_mul_f32_e32 v130, 0xbfb8aa3b, v76
	v_mul_f32_e32 v131, 0xbfb8aa3b, v77
	v_mul_f32_e32 v132, 0xbfb8aa3b, v78
	v_mul_f32_e32 v133, 0xbfb8aa3b, v79
	v_exp_f32_e32 v130, v130
	v_exp_f32_e32 v131, v131
	v_exp_f32_e32 v132, v132
	v_exp_f32_e32 v133, v133
	v_exp_f32_e32 v138, v138
	v_exp_f32_e32 v139, v139
	v_mul_f32_e32 v140, 0xbfb8aa3b, v74
	v_mul_f32_e32 v141, 0xbfb8aa3b, v75
	v_add_f32_e32 v130, 1.0, v130
	v_add_f32_e32 v131, 1.0, v131
	v_add_f32_e32 v132, 1.0, v132
	v_add_f32_e32 v133, 1.0, v133
	v_add_f32_e32 v138, 1.0, v138
	v_add_f32_e32 v139, 1.0, v139
	v_exp_f32_e32 v140, v140
	v_exp_f32_e32 v141, v141
	v_rcp_f32_e32 v130, v130
	v_rcp_f32_e32 v131, v131
	v_rcp_f32_e32 v132, v132
	v_rcp_f32_e32 v133, v133
	v_rcp_f32_e32 v138, v138
	v_rcp_f32_e32 v139, v139
	v_add_f32_e32 v140, 1.0, v140
	v_add_f32_e32 v141, 1.0, v141
	v_rcp_f32_e32 v140, v140
	v_rcp_f32_e32 v141, v141
	v_pk_mul_f32 v[130:131], v[76:77], v[130:131]
	v_pk_mul_f32 v[132:133], v[78:79], v[132:133]
	v_pk_mul_f32 v[138:139], v[72:73], v[138:139]
	v_cvt_pk_bf16_f32 v130, v130, v131
	v_cvt_pk_bf16_f32 v131, v132, v133
	v_cvt_pk_bf16_f32 v132, v138, v139
	v_mul_f32_e32 v138, 0xbfb8aa3b, v68
	v_mul_f32_e32 v139, 0xbfb8aa3b, v69
	v_exp_f32_e32 v138, v138
	v_exp_f32_e32 v139, v139
	v_lshl_add_u64 v[136:137], v[134:135], 0, s[10:11]
	v_pk_mul_f32 v[140:141], v[74:75], v[140:141]
	v_add_co_u32_e32 v134, vcc, s8, v134
	v_cvt_pk_bf16_f32 v133, v140, v141
	s_nop 0
	v_addc_co_u32_e32 v135, vcc, 0, v135, vcc
	flat_store_dwordx4 v[134:135], v[130:133] offset:2048 sc1
	v_mul_f32_e32 v134, 0xbfb8aa3b, v64
	v_mul_f32_e32 v135, 0xbfb8aa3b, v65
	v_add_f32_e32 v130, 1.0, v138
	v_add_f32_e32 v131, 1.0, v139
	v_mul_f32_e32 v132, 0xbfb8aa3b, v70
	v_mul_f32_e32 v133, 0xbfb8aa3b, v71
	v_mul_f32_e32 v138, 0xbfb8aa3b, v66
	v_mul_f32_e32 v139, 0xbfb8aa3b, v67
	v_exp_f32_e32 v132, v132
	v_exp_f32_e32 v133, v133
	v_exp_f32_e32 v134, v134
	v_exp_f32_e32 v135, v135
	v_exp_f32_e32 v138, v138
	v_exp_f32_e32 v139, v139
	v_add_f32_e32 v132, 1.0, v132
	v_add_f32_e32 v133, 1.0, v133
	v_add_f32_e32 v134, 1.0, v134
	v_add_f32_e32 v135, 1.0, v135
	v_add_f32_e32 v138, 1.0, v138
	v_add_f32_e32 v139, 1.0, v139
	v_rcp_f32_e32 v130, v130
	v_rcp_f32_e32 v131, v131
	v_rcp_f32_e32 v132, v132
	v_rcp_f32_e32 v133, v133
	v_rcp_f32_e32 v134, v134
	v_rcp_f32_e32 v135, v135
	v_rcp_f32_e32 v138, v138
	v_rcp_f32_e32 v139, v139
	v_pk_mul_f32 v[130:131], v[68:69], v[130:131]
	v_pk_mul_f32 v[132:133], v[70:71], v[132:133]
	v_pk_mul_f32 v[134:135], v[64:65], v[134:135]
	v_pk_mul_f32 v[138:139], v[66:67], v[138:139]
	v_cvt_pk_bf16_f32 v130, v130, v131
	v_cvt_pk_bf16_f32 v131, v132, v133
	v_cvt_pk_bf16_f32 v132, v134, v135
	v_cvt_pk_bf16_f32 v133, v138, v139
	flat_store_dwordx4 v[136:137], v[130:133] offset:256 sc1
	v_mul_f32_e32 v138, 0xbfb8aa3b, v58
	v_mul_f32_e32 v139, 0xbfb8aa3b, v59
	v_mul_f32_e32 v130, 0xbfb8aa3b, v60
	v_mul_f32_e32 v131, 0xbfb8aa3b, v61
	v_mul_f32_e32 v132, 0xbfb8aa3b, v62
	v_mul_f32_e32 v133, 0xbfb8aa3b, v63
	v_exp_f32_e32 v130, v130
	v_exp_f32_e32 v131, v131
	v_exp_f32_e32 v132, v132
	v_exp_f32_e32 v133, v133
	v_exp_f32_e32 v138, v138
	v_exp_f32_e32 v139, v139
	v_mul_f32_e32 v136, 0xbfb8aa3b, v56
	v_mul_f32_e32 v137, 0xbfb8aa3b, v57
	v_exp_f32_e32 v136, v136
	v_exp_f32_e32 v137, v137
	v_add_f32_e32 v130, 1.0, v130
	v_add_f32_e32 v131, 1.0, v131
	v_add_f32_e32 v132, 1.0, v132
	v_add_f32_e32 v133, 1.0, v133
	v_add_f32_e32 v138, 1.0, v138
	v_add_f32_e32 v139, 1.0, v139
	v_rcp_f32_e32 v130, v130
	v_rcp_f32_e32 v131, v131
	v_rcp_f32_e32 v132, v132
	v_rcp_f32_e32 v133, v133
	v_rcp_f32_e32 v138, v138
	v_rcp_f32_e32 v139, v139
	v_add_f32_e32 v136, 1.0, v136
	v_add_f32_e32 v137, 1.0, v137
	v_rcp_f32_e32 v136, v136
	v_rcp_f32_e32 v137, v137
	v_pk_mul_f32 v[130:131], v[60:61], v[130:131]
	v_pk_mul_f32 v[132:133], v[62:63], v[132:133]
	v_pk_mul_f32 v[138:139], v[58:59], v[138:139]
	v_cvt_pk_bf16_f32 v130, v130, v131
	v_cvt_pk_bf16_f32 v131, v132, v133
	v_cvt_pk_bf16_f32 v133, v138, v139
	v_mul_f32_e32 v138, 0xbfb8aa3b, v52
	v_mul_f32_e32 v139, 0xbfb8aa3b, v53
	v_exp_f32_e32 v138, v138
	v_exp_f32_e32 v139, v139
	v_pk_mul_f32 v[136:137], v[56:57], v[136:137]
	s_mov_b32 s2, 0xef3e000
	v_cvt_pk_bf16_f32 v132, v136, v137
	v_add_co_u32_e32 v136, vcc, s2, v128
	s_mov_b64 s[8:9], 0xef3e800
	s_nop 0
	v_addc_co_u32_e32 v137, vcc, 0, v129, vcc
	flat_store_dwordx4 v[136:137], v[130:133] offset:2048 sc1
	v_mul_f32_e32 v136, 0xbfb8aa3b, v48
	v_mul_f32_e32 v137, 0xbfb8aa3b, v49
	v_add_f32_e32 v130, 1.0, v138
	v_add_f32_e32 v131, 1.0, v139
	v_mul_f32_e32 v132, 0xbfb8aa3b, v54
	v_mul_f32_e32 v133, 0xbfb8aa3b, v55
	v_mul_f32_e32 v138, 0xbfb8aa3b, v50
	v_mul_f32_e32 v139, 0xbfb8aa3b, v51
	v_exp_f32_e32 v132, v132
	v_exp_f32_e32 v133, v133
	v_exp_f32_e32 v136, v136
	v_exp_f32_e32 v137, v137
	v_exp_f32_e32 v138, v138
	v_exp_f32_e32 v139, v139
	v_add_f32_e32 v132, 1.0, v132
	v_add_f32_e32 v133, 1.0, v133
	v_add_f32_e32 v136, 1.0, v136
	v_add_f32_e32 v137, 1.0, v137
	v_add_f32_e32 v138, 1.0, v138
	v_add_f32_e32 v139, 1.0, v139
	v_rcp_f32_e32 v130, v130
	v_rcp_f32_e32 v131, v131
	v_rcp_f32_e32 v132, v132
	v_rcp_f32_e32 v133, v133
	v_rcp_f32_e32 v136, v136
	v_rcp_f32_e32 v137, v137
	v_rcp_f32_e32 v138, v138
	v_rcp_f32_e32 v139, v139
	v_pk_mul_f32 v[130:131], v[52:53], v[130:131]
	v_pk_mul_f32 v[132:133], v[54:55], v[132:133]
	v_pk_mul_f32 v[136:137], v[48:49], v[136:137]
	v_pk_mul_f32 v[138:139], v[50:51], v[138:139]
	v_lshl_add_u64 v[134:135], v[128:129], 0, s[8:9]
	v_cvt_pk_bf16_f32 v130, v130, v131
	v_cvt_pk_bf16_f32 v131, v132, v133
	v_cvt_pk_bf16_f32 v132, v136, v137
	v_cvt_pk_bf16_f32 v133, v138, v139
	flat_store_dwordx4 v[134:135], v[130:133] offset:256 sc1
	v_mul_f32_e32 v138, 0xbfb8aa3b, v42
	v_mul_f32_e32 v139, 0xbfb8aa3b, v43
	v_mul_f32_e32 v130, 0xbfb8aa3b, v44
	v_mul_f32_e32 v131, 0xbfb8aa3b, v45
	v_mul_f32_e32 v132, 0xbfb8aa3b, v46
	v_mul_f32_e32 v133, 0xbfb8aa3b, v47
	v_exp_f32_e32 v130, v130
	v_exp_f32_e32 v131, v131
	v_exp_f32_e32 v132, v132
	v_exp_f32_e32 v133, v133
	v_exp_f32_e32 v138, v138
	v_exp_f32_e32 v139, v139
	v_mul_f32_e32 v136, 0xbfb8aa3b, v40
	v_mul_f32_e32 v137, 0xbfb8aa3b, v41
	v_exp_f32_e32 v136, v136
	v_exp_f32_e32 v137, v137
	v_add_f32_e32 v130, 1.0, v130
	v_add_f32_e32 v131, 1.0, v131
	v_add_f32_e32 v132, 1.0, v132
	v_add_f32_e32 v133, 1.0, v133
	v_add_f32_e32 v138, 1.0, v138
	v_add_f32_e32 v139, 1.0, v139
	v_rcp_f32_e32 v130, v130
	v_rcp_f32_e32 v131, v131
	v_rcp_f32_e32 v132, v132
	v_rcp_f32_e32 v133, v133
	v_rcp_f32_e32 v138, v138
	v_rcp_f32_e32 v139, v139
	v_add_f32_e32 v136, 1.0, v136
	v_add_f32_e32 v137, 1.0, v137
	v_rcp_f32_e32 v136, v136
	v_rcp_f32_e32 v137, v137
	v_pk_mul_f32 v[130:131], v[44:45], v[130:131]
	v_pk_mul_f32 v[132:133], v[46:47], v[132:133]
	v_pk_mul_f32 v[138:139], v[42:43], v[138:139]
	v_cvt_pk_bf16_f32 v130, v130, v131
	v_cvt_pk_bf16_f32 v131, v132, v133
	v_cvt_pk_bf16_f32 v133, v138, v139
	v_mul_f32_e32 v138, 0xbfb8aa3b, v36
	v_mul_f32_e32 v139, 0xbfb8aa3b, v37
	v_exp_f32_e32 v138, v138
	v_exp_f32_e32 v139, v139
	v_pk_mul_f32 v[136:137], v[40:41], v[136:137]
	s_mov_b32 s2, 0xef46000
	v_cvt_pk_bf16_f32 v132, v136, v137
	v_add_co_u32_e32 v136, vcc, s2, v128
	s_mov_b64 s[8:9], 0xef46800
	s_nop 0
	v_addc_co_u32_e32 v137, vcc, 0, v129, vcc
	flat_store_dwordx4 v[136:137], v[130:133] offset:2048 sc1
	v_mul_f32_e32 v136, 0xbfb8aa3b, v32
	v_mul_f32_e32 v137, 0xbfb8aa3b, v33
	v_add_f32_e32 v130, 1.0, v138
	v_add_f32_e32 v131, 1.0, v139
	v_mul_f32_e32 v132, 0xbfb8aa3b, v38
	v_mul_f32_e32 v133, 0xbfb8aa3b, v39
	v_mul_f32_e32 v138, 0xbfb8aa3b, v34
	v_mul_f32_e32 v139, 0xbfb8aa3b, v35
	v_exp_f32_e32 v132, v132
	v_exp_f32_e32 v133, v133
	v_exp_f32_e32 v136, v136
	v_exp_f32_e32 v137, v137
	v_exp_f32_e32 v138, v138
	v_exp_f32_e32 v139, v139
	v_add_f32_e32 v132, 1.0, v132
	v_add_f32_e32 v133, 1.0, v133
	v_add_f32_e32 v136, 1.0, v136
	v_add_f32_e32 v137, 1.0, v137
	v_add_f32_e32 v138, 1.0, v138
	v_add_f32_e32 v139, 1.0, v139
	v_rcp_f32_e32 v130, v130
	v_rcp_f32_e32 v131, v131
	v_rcp_f32_e32 v132, v132
	v_rcp_f32_e32 v133, v133
	v_rcp_f32_e32 v136, v136
	v_rcp_f32_e32 v137, v137
	v_rcp_f32_e32 v138, v138
	v_rcp_f32_e32 v139, v139
	v_pk_mul_f32 v[130:131], v[36:37], v[130:131]
	v_pk_mul_f32 v[132:133], v[38:39], v[132:133]
	v_pk_mul_f32 v[136:137], v[32:33], v[136:137]
	v_pk_mul_f32 v[138:139], v[34:35], v[138:139]
	v_lshl_add_u64 v[134:135], v[128:129], 0, s[8:9]
	v_cvt_pk_bf16_f32 v130, v130, v131
	v_cvt_pk_bf16_f32 v131, v132, v133
	v_cvt_pk_bf16_f32 v132, v136, v137
	v_cvt_pk_bf16_f32 v133, v138, v139
	flat_store_dwordx4 v[134:135], v[130:133] offset:256 sc1
	v_mul_f32_e32 v138, 0xbfb8aa3b, v26
	v_mul_f32_e32 v139, 0xbfb8aa3b, v27
	v_mul_f32_e32 v130, 0xbfb8aa3b, v28
	v_mul_f32_e32 v131, 0xbfb8aa3b, v29
	v_mul_f32_e32 v132, 0xbfb8aa3b, v30
	v_mul_f32_e32 v133, 0xbfb8aa3b, v31
	v_exp_f32_e32 v130, v130
	v_exp_f32_e32 v131, v131
	v_exp_f32_e32 v132, v132
	v_exp_f32_e32 v133, v133
	v_exp_f32_e32 v138, v138
	v_exp_f32_e32 v139, v139
	v_mul_f32_e32 v136, 0xbfb8aa3b, v24
	v_mul_f32_e32 v137, 0xbfb8aa3b, v25
	v_exp_f32_e32 v136, v136
	v_exp_f32_e32 v137, v137
	v_add_f32_e32 v130, 1.0, v130
	v_add_f32_e32 v131, 1.0, v131
	v_add_f32_e32 v132, 1.0, v132
	v_add_f32_e32 v133, 1.0, v133
	v_add_f32_e32 v138, 1.0, v138
	v_add_f32_e32 v139, 1.0, v139
	v_rcp_f32_e32 v130, v130
	v_rcp_f32_e32 v131, v131
	v_rcp_f32_e32 v132, v132
	v_rcp_f32_e32 v133, v133
	v_rcp_f32_e32 v138, v138
	v_rcp_f32_e32 v139, v139
	v_add_f32_e32 v136, 1.0, v136
	v_add_f32_e32 v137, 1.0, v137
	v_rcp_f32_e32 v136, v136
	v_rcp_f32_e32 v137, v137
	v_pk_mul_f32 v[130:131], v[28:29], v[130:131]
	v_pk_mul_f32 v[132:133], v[30:31], v[132:133]
	v_pk_mul_f32 v[138:139], v[26:27], v[138:139]
	v_cvt_pk_bf16_f32 v130, v130, v131
	v_cvt_pk_bf16_f32 v131, v132, v133
	v_cvt_pk_bf16_f32 v133, v138, v139
	v_mul_f32_e32 v138, 0xbfb8aa3b, v20
	v_mul_f32_e32 v139, 0xbfb8aa3b, v21
	v_exp_f32_e32 v138, v138
	v_exp_f32_e32 v139, v139
	v_pk_mul_f32 v[136:137], v[24:25], v[136:137]
	s_mov_b32 s2, 0xef4e000
	v_cvt_pk_bf16_f32 v132, v136, v137
	v_add_co_u32_e32 v136, vcc, s2, v128
	s_mov_b64 s[8:9], 0xef4e800
	s_nop 0
	v_addc_co_u32_e32 v137, vcc, 0, v129, vcc
	flat_store_dwordx4 v[136:137], v[130:133] offset:2048 sc1
	v_mul_f32_e32 v136, 0xbfb8aa3b, v16
	v_mul_f32_e32 v137, 0xbfb8aa3b, v17
	v_add_f32_e32 v130, 1.0, v138
	v_add_f32_e32 v131, 1.0, v139
	v_mul_f32_e32 v132, 0xbfb8aa3b, v22
	v_mul_f32_e32 v133, 0xbfb8aa3b, v23
	v_mul_f32_e32 v138, 0xbfb8aa3b, v18
	v_mul_f32_e32 v139, 0xbfb8aa3b, v19
	v_exp_f32_e32 v132, v132
	v_exp_f32_e32 v133, v133
	v_exp_f32_e32 v136, v136
	v_exp_f32_e32 v137, v137
	v_exp_f32_e32 v138, v138
	v_exp_f32_e32 v139, v139
	v_add_f32_e32 v132, 1.0, v132
	v_add_f32_e32 v133, 1.0, v133
	v_add_f32_e32 v136, 1.0, v136
	v_add_f32_e32 v137, 1.0, v137
	v_add_f32_e32 v138, 1.0, v138
	v_add_f32_e32 v139, 1.0, v139
	v_rcp_f32_e32 v130, v130
	v_rcp_f32_e32 v131, v131
	v_rcp_f32_e32 v132, v132
	v_rcp_f32_e32 v133, v133
	v_rcp_f32_e32 v136, v136
	v_rcp_f32_e32 v137, v137
	v_rcp_f32_e32 v138, v138
	v_rcp_f32_e32 v139, v139
	v_pk_mul_f32 v[130:131], v[20:21], v[130:131]
	v_pk_mul_f32 v[132:133], v[22:23], v[132:133]
	v_pk_mul_f32 v[136:137], v[16:17], v[136:137]
	v_pk_mul_f32 v[138:139], v[18:19], v[138:139]
	v_lshl_add_u64 v[134:135], v[128:129], 0, s[8:9]
	v_cvt_pk_bf16_f32 v130, v130, v131
	v_cvt_pk_bf16_f32 v131, v132, v133
	v_cvt_pk_bf16_f32 v132, v136, v137
	v_cvt_pk_bf16_f32 v133, v138, v139
	flat_store_dwordx4 v[134:135], v[130:133] offset:256 sc1
	v_mul_f32_e32 v136, 0xbfb8aa3b, v8
	v_mul_f32_e32 v137, 0xbfb8aa3b, v9
	v_mul_f32_e32 v130, 0xbfb8aa3b, v12
	v_mul_f32_e32 v131, 0xbfb8aa3b, v13
	v_mul_f32_e32 v132, 0xbfb8aa3b, v14
	v_mul_f32_e32 v133, 0xbfb8aa3b, v15
	v_exp_f32_e32 v130, v130
	v_exp_f32_e32 v131, v131
	v_exp_f32_e32 v132, v132
	v_exp_f32_e32 v133, v133
	v_exp_f32_e32 v136, v136
	v_exp_f32_e32 v137, v137
	v_mul_f32_e32 v138, 0xbfb8aa3b, v10
	v_mul_f32_e32 v139, 0xbfb8aa3b, v11
	v_add_f32_e32 v130, 1.0, v130
	v_add_f32_e32 v131, 1.0, v131
	v_add_f32_e32 v132, 1.0, v132
	v_add_f32_e32 v133, 1.0, v133
	v_add_f32_e32 v136, 1.0, v136
	v_add_f32_e32 v137, 1.0, v137
	v_exp_f32_e32 v138, v138
	v_exp_f32_e32 v139, v139
	v_rcp_f32_e32 v130, v130
	v_rcp_f32_e32 v131, v131
	v_rcp_f32_e32 v132, v132
	v_rcp_f32_e32 v133, v133
	v_rcp_f32_e32 v136, v136
	v_rcp_f32_e32 v137, v137
	v_add_f32_e32 v138, 1.0, v138
	v_add_f32_e32 v139, 1.0, v139
	v_rcp_f32_e32 v138, v138
	v_rcp_f32_e32 v139, v139
	v_pk_mul_f32 v[130:131], v[12:13], v[130:131]
	v_pk_mul_f32 v[132:133], v[14:15], v[132:133]
	v_pk_mul_f32 v[136:137], v[8:9], v[136:137]
	v_cvt_pk_bf16_f32 v130, v130, v131
	v_cvt_pk_bf16_f32 v131, v132, v133
	v_cvt_pk_bf16_f32 v132, v136, v137
	v_mul_f32_e32 v136, 0xbfb8aa3b, v4
	v_mul_f32_e32 v137, 0xbfb8aa3b, v5
	v_exp_f32_e32 v136, v136
	v_exp_f32_e32 v137, v137
	s_mov_b64 s[8:9], 0xef56800
	s_mov_b32 s2, 0xef56000
	v_lshl_add_u64 v[134:135], v[128:129], 0, s[8:9]
	v_pk_mul_f32 v[138:139], v[10:11], v[138:139]
	v_add_co_u32_e32 v128, vcc, s2, v128
	v_cvt_pk_bf16_f32 v133, v138, v139
	s_nop 0
	v_addc_co_u32_e32 v129, vcc, 0, v129, vcc
	flat_store_dwordx4 v[128:129], v[130:133] offset:2048 sc1
	v_add_f32_e32 v128, 1.0, v136
	v_add_f32_e32 v129, 1.0, v137
	v_mul_f32_e32 v130, 0xbfb8aa3b, v6
	v_mul_f32_e32 v131, 0xbfb8aa3b, v7
	v_mul_f32_e32 v132, 0xbfb8aa3b, v0
	v_mul_f32_e32 v133, 0xbfb8aa3b, v1
	v_mul_f32_e32 v136, 0xbfb8aa3b, v2
	v_mul_f32_e32 v137, 0xbfb8aa3b, v3
	v_exp_f32_e32 v130, v130
	v_exp_f32_e32 v131, v131
	v_exp_f32_e32 v132, v132
	v_exp_f32_e32 v133, v133
	v_exp_f32_e32 v136, v136
	v_exp_f32_e32 v137, v137
	v_add_f32_e32 v130, 1.0, v130
	v_add_f32_e32 v131, 1.0, v131
	v_add_f32_e32 v132, 1.0, v132
	v_add_f32_e32 v133, 1.0, v133
	v_add_f32_e32 v136, 1.0, v136
	v_add_f32_e32 v137, 1.0, v137
	v_rcp_f32_e32 v128, v128
	v_rcp_f32_e32 v129, v129
	v_rcp_f32_e32 v130, v130
	v_rcp_f32_e32 v131, v131
	v_rcp_f32_e32 v132, v132
	v_rcp_f32_e32 v133, v133
	v_rcp_f32_e32 v136, v136
	v_rcp_f32_e32 v137, v137
	v_pk_mul_f32 v[128:129], v[4:5], v[128:129]
	v_pk_mul_f32 v[130:131], v[6:7], v[130:131]
	v_pk_mul_f32 v[132:133], v[0:1], v[132:133]
	v_pk_mul_f32 v[136:137], v[2:3], v[136:137]
	v_cvt_pk_bf16_f32 v128, v128, v129
	v_cvt_pk_bf16_f32 v129, v130, v131
	v_cvt_pk_bf16_f32 v130, v132, v133
	v_cvt_pk_bf16_f32 v131, v136, v137
	flat_store_dwordx4 v[134:135], v[128:131] offset:256 sc1

.LBB0_1127:
	s_andn2_b64 vcc, exec, s[8:9]
	s_cbranch_vccnz .LBB0_1129
	v_ashrrev_i32_e32 v173, 31, v172
	v_lshlrev_b64 v[128:129], 10, v[172:173]
	v_lshl_add_u64 v[128:129], s[18:19], 0, v[128:129]
	s_lshl_b32 s2, s14, 9
	v_lshl_add_u64 v[128:129], v[128:129], 0, s[2:3]
	v_lshlrev_b32_e32 v152, 1, v186
	v_lshl_add_u64 v[132:133], v[128:129], 0, v[152:153]
	s_mov_b32 s8, 0xc6ff000
	s_waitcnt lgkmcnt(0)
	v_add_co_u32_e32 v136, vcc, s8, v132
	s_mov_b64 s[10:11], 0xc6ff800
	v_cvt_pk_bf16_f32 v128, v124, v125
	v_cvt_pk_bf16_f32 v129, v126, v127
	v_cvt_pk_bf16_f32 v130, v120, v121
	v_cvt_pk_bf16_f32 v131, v122, v123
	v_addc_co_u32_e32 v137, vcc, 0, v133, vcc
	v_lshl_add_u64 v[134:135], v[132:133], 0, s[10:11]
	flat_store_dwordx4 v[136:137], v[128:131] offset:2048 sc1
	s_nop 1
	v_cvt_pk_bf16_f32 v128, v116, v117
	v_cvt_pk_bf16_f32 v129, v118, v119
	v_cvt_pk_bf16_f32 v130, v112, v113
	v_cvt_pk_bf16_f32 v131, v114, v115
	flat_store_dwordx4 v[134:135], v[128:131] offset:256 sc1
	s_nop 1
	v_or_b32_e32 v128, 16, v172
	v_ashrrev_i32_e32 v129, 31, v128
	v_lshlrev_b64 v[128:129], 10, v[128:129]
	v_lshl_add_u64 v[128:129], s[18:19], 0, v[128:129]
	v_lshl_add_u64 v[128:129], v[128:129], 0, s[2:3]
	v_lshl_add_u64 v[134:135], v[128:129], 0, v[152:153]
	v_lshl_add_u64 v[136:137], v[134:135], 0, s[10:11]
	v_add_co_u32_e32 v134, vcc, s8, v134
	v_cvt_pk_bf16_f32 v128, v108, v109
	v_cvt_pk_bf16_f32 v129, v110, v111
	v_cvt_pk_bf16_f32 v130, v104, v105
	v_cvt_pk_bf16_f32 v131, v106, v107
	v_addc_co_u32_e32 v135, vcc, 0, v135, vcc
	flat_store_dwordx4 v[134:135], v[128:131] offset:2048 sc1
	s_nop 1
	v_cvt_pk_bf16_f32 v128, v100, v101
	v_cvt_pk_bf16_f32 v129, v102, v103
	v_cvt_pk_bf16_f32 v130, v96, v97
	v_cvt_pk_bf16_f32 v131, v98, v99
	flat_store_dwordx4 v[136:137], v[128:131] offset:256 sc1
	s_nop 1
	v_or_b32_e32 v128, 32, v172
	v_ashrrev_i32_e32 v129, 31, v128
	v_lshlrev_b64 v[128:129], 10, v[128:129]
	v_lshl_add_u64 v[128:129], s[18:19], 0, v[128:129]
	v_lshl_add_u64 v[128:129], v[128:129], 0, s[2:3]
	v_lshl_add_u64 v[134:135], v[128:129], 0, v[152:153]
	v_lshl_add_u64 v[136:137], v[134:135], 0, s[10:11]
	v_add_co_u32_e32 v134, vcc, s8, v134
	v_cvt_pk_bf16_f32 v128, v92, v93
	v_cvt_pk_bf16_f32 v129, v94, v95
	v_cvt_pk_bf16_f32 v130, v88, v89
	v_cvt_pk_bf16_f32 v131, v90, v91
	v_addc_co_u32_e32 v135, vcc, 0, v135, vcc
	flat_store_dwordx4 v[134:135], v[128:131] offset:2048 sc1
	s_nop 1
	v_cvt_pk_bf16_f32 v128, v84, v85
	v_cvt_pk_bf16_f32 v129, v86, v87
	v_cvt_pk_bf16_f32 v130, v80, v81
	v_cvt_pk_bf16_f32 v131, v82, v83
	flat_store_dwordx4 v[136:137], v[128:131] offset:256 sc1
	s_nop 1
	v_or_b32_e32 v128, 48, v172
	v_ashrrev_i32_e32 v129, 31, v128
	v_lshlrev_b64 v[128:129], 10, v[128:129]
	v_lshl_add_u64 v[128:129], s[18:19], 0, v[128:129]
	v_lshl_add_u64 v[128:129], v[128:129], 0, s[2:3]
	v_lshl_add_u64 v[134:135], v[128:129], 0, v[152:153]
	v_lshl_add_u64 v[136:137], v[134:135], 0, s[10:11]
	v_add_co_u32_e32 v134, vcc, s8, v134
	v_cvt_pk_bf16_f32 v128, v76, v77
	v_cvt_pk_bf16_f32 v129, v78, v79
	v_cvt_pk_bf16_f32 v130, v72, v73
	v_cvt_pk_bf16_f32 v131, v74, v75
	v_addc_co_u32_e32 v135, vcc, 0, v135, vcc
	flat_store_dwordx4 v[134:135], v[128:131] offset:2048 sc1
	s_mov_b32 s2, 0xc71f000
	s_mov_b64 s[8:9], 0xc71f800
	v_cvt_pk_bf16_f32 v128, v68, v69
	v_cvt_pk_bf16_f32 v129, v70, v71
	v_cvt_pk_bf16_f32 v130, v64, v65
	v_cvt_pk_bf16_f32 v131, v66, v67
	flat_store_dwordx4 v[136:137], v[128:131] offset:256 sc1
	v_add_co_u32_e32 v136, vcc, s2, v132
	s_nop 0
	v_cvt_pk_bf16_f32 v128, v60, v61
	v_cvt_pk_bf16_f32 v129, v62, v63
	v_cvt_pk_bf16_f32 v130, v56, v57
	v_cvt_pk_bf16_f32 v131, v58, v59
	v_addc_co_u32_e32 v137, vcc, 0, v133, vcc
	s_mov_b32 s2, 0xc723000
	v_lshl_add_u64 v[134:135], v[132:133], 0, s[8:9]
	flat_store_dwordx4 v[136:137], v[128:131] offset:2048 sc1
	v_add_co_u32_e32 v136, vcc, s2, v132
	s_nop 0
	v_cvt_pk_bf16_f32 v128, v52, v53
	v_cvt_pk_bf16_f32 v129, v54, v55
	v_cvt_pk_bf16_f32 v130, v48, v49
	v_cvt_pk_bf16_f32 v131, v50, v51
	flat_store_dwordx4 v[134:135], v[128:131] offset:256 sc1
	s_mov_b64 s[8:9], 0xc723800
	v_addc_co_u32_e32 v137, vcc, 0, v133, vcc
	v_cvt_pk_bf16_f32 v128, v44, v45
	v_cvt_pk_bf16_f32 v129, v46, v47
	v_cvt_pk_bf16_f32 v130, v40, v41
	v_cvt_pk_bf16_f32 v131, v42, v43
	s_mov_b32 s2, 0xc727000
	v_lshl_add_u64 v[134:135], v[132:133], 0, s[8:9]
	flat_store_dwordx4 v[136:137], v[128:131] offset:2048 sc1
	v_add_co_u32_e32 v136, vcc, s2, v132
	s_nop 0
	v_cvt_pk_bf16_f32 v128, v36, v37
	v_cvt_pk_bf16_f32 v129, v38, v39
	v_cvt_pk_bf16_f32 v130, v32, v33
	v_cvt_pk_bf16_f32 v131, v34, v35
	flat_store_dwordx4 v[134:135], v[128:131] offset:256 sc1
	s_mov_b64 s[8:9], 0xc727800
	v_addc_co_u32_e32 v137, vcc, 0, v133, vcc
	v_cvt_pk_bf16_f32 v128, v28, v29
	v_cvt_pk_bf16_f32 v129, v30, v31
	v_cvt_pk_bf16_f32 v130, v24, v25
	v_cvt_pk_bf16_f32 v131, v26, v27
	v_lshl_add_u64 v[134:135], v[132:133], 0, s[8:9]
	flat_store_dwordx4 v[136:137], v[128:131] offset:2048 sc1
	s_mov_b64 s[8:9], 0xc72b800
	s_mov_b32 s2, 0xc72b000
	v_cvt_pk_bf16_f32 v128, v20, v21
	v_cvt_pk_bf16_f32 v129, v22, v23
	v_cvt_pk_bf16_f32 v130, v16, v17
	v_cvt_pk_bf16_f32 v131, v18, v19
	flat_store_dwordx4 v[134:135], v[128:131] offset:256 sc1
	v_lshl_add_u64 v[134:135], v[132:133], 0, s[8:9]
	v_add_co_u32_e32 v132, vcc, s2, v132
	v_cvt_pk_bf16_f32 v128, v12, v13
	v_cvt_pk_bf16_f32 v129, v14, v15
	v_cvt_pk_bf16_f32 v130, v8, v9
	v_cvt_pk_bf16_f32 v131, v10, v11
	v_addc_co_u32_e32 v133, vcc, 0, v133, vcc
	flat_store_dwordx4 v[132:133], v[128:131] offset:2048 sc1
	s_nop 1
	v_cvt_pk_bf16_f32 v128, v4, v5
	v_cvt_pk_bf16_f32 v129, v6, v7
	v_cvt_pk_bf16_f32 v130, v0, v1
	v_cvt_pk_bf16_f32 v131, v2, v3
	flat_store_dwordx4 v[134:135], v[128:131] offset:256 sc1

.LBB0_1130:
	s_andn2_b64 vcc, exec, s[8:9]
	s_cbranch_vccnz .LBB0_1132
	v_mul_f32_e32 v130, 0xbfb8aa3b, v116
	v_mul_f32_e32 v131, 0xbfb8aa3b, v117
	v_mul_f32_e32 v132, 0xbfb8aa3b, v118
	v_mul_f32_e32 v133, 0xbfb8aa3b, v119
	v_mul_f32_e32 v134, 0xbfb8aa3b, v112
	v_mul_f32_e32 v135, 0xbfb8aa3b, v113
	s_waitcnt lgkmcnt(0)
	v_mul_f32_e32 v136, 0xbfb8aa3b, v114
	v_mul_f32_e32 v137, 0xbfb8aa3b, v115
	v_exp_f32_e32 v130, v130
	v_exp_f32_e32 v131, v131
	v_exp_f32_e32 v132, v132
	v_exp_f32_e32 v133, v133
	v_exp_f32_e32 v134, v134
	v_exp_f32_e32 v135, v135
	v_exp_f32_e32 v136, v136
	v_exp_f32_e32 v137, v137
	v_add_f32_e32 v130, 1.0, v130
	v_add_f32_e32 v131, 1.0, v131
	v_add_f32_e32 v132, 1.0, v132
	v_add_f32_e32 v133, 1.0, v133
	v_add_f32_e32 v134, 1.0, v134
	v_add_f32_e32 v135, 1.0, v135
	v_add_f32_e32 v136, 1.0, v136
	v_add_f32_e32 v137, 1.0, v137
	v_rcp_f32_e32 v130, v130
	v_rcp_f32_e32 v131, v131
	v_rcp_f32_e32 v132, v132
	v_rcp_f32_e32 v133, v133
	v_rcp_f32_e32 v134, v134
	v_rcp_f32_e32 v135, v135
	v_rcp_f32_e32 v136, v136
	v_rcp_f32_e32 v137, v137
	s_lshl_b32 s8, s14, 7
	v_ashrrev_i32_e32 v173, 31, v172
	v_readlane_b32 s10, v254, 35
	s_ashr_i32 s9, s8, 31
	v_lshlrev_b64 v[128:129], 10, v[172:173]
	v_readlane_b32 s11, v254, 36
	s_lshl_b64 s[8:9], s[8:9], 1
	v_pk_mul_f32 v[130:131], v[124:125], v[130:131]
	v_lshl_add_u64 v[128:129], s[10:11], 0, v[128:129]
	v_lshl_add_u64 v[128:129], v[128:129], 0, s[8:9]
	v_pk_mul_f32 v[132:133], v[126:127], v[132:133]
	v_pk_mul_f32 v[134:135], v[120:121], v[134:135]
	v_pk_mul_f32 v[136:137], v[122:123], v[136:137]
	v_lshlrev_b32_e32 v152, 1, v186
	v_lshl_add_u64 v[128:129], v[128:129], 0, v[152:153]
	v_cvt_pk_bf16_f32 v130, v130, v131
	v_cvt_pk_bf16_f32 v131, v132, v133
	v_cvt_pk_bf16_f32 v132, v134, v135
	v_cvt_pk_bf16_f32 v133, v136, v137
	flat_store_dwordx4 v[128:129], v[130:133] sc1
	v_mul_f32_e32 v134, 0xbfb8aa3b, v102
	v_mul_f32_e32 v135, 0xbfb8aa3b, v103
	v_mul_f32_e32 v132, 0xbfb8aa3b, v100
	v_mul_f32_e32 v133, 0xbfb8aa3b, v101
	v_mul_f32_e32 v136, 0xbfb8aa3b, v96
	v_mul_f32_e32 v137, 0xbfb8aa3b, v97
	v_mul_f32_e32 v138, 0xbfb8aa3b, v98
	v_mul_f32_e32 v139, 0xbfb8aa3b, v99
	v_exp_f32_e32 v132, v132
	v_exp_f32_e32 v133, v133
	v_exp_f32_e32 v134, v134
	v_exp_f32_e32 v135, v135
	v_exp_f32_e32 v136, v136
	v_exp_f32_e32 v137, v137
	v_exp_f32_e32 v138, v138
	v_exp_f32_e32 v139, v139
	v_add_f32_e32 v132, 1.0, v132
	v_add_f32_e32 v133, 1.0, v133
	v_add_f32_e32 v134, 1.0, v134
	v_add_f32_e32 v135, 1.0, v135
	v_add_f32_e32 v136, 1.0, v136
	v_add_f32_e32 v137, 1.0, v137
	v_add_f32_e32 v138, 1.0, v138
	v_add_f32_e32 v139, 1.0, v139
	v_or_b32_e32 v130, 16, v172
	v_rcp_f32_e32 v132, v132
	v_rcp_f32_e32 v133, v133
	v_rcp_f32_e32 v134, v134
	v_rcp_f32_e32 v135, v135
	v_rcp_f32_e32 v136, v136
	v_rcp_f32_e32 v137, v137
	v_rcp_f32_e32 v138, v138
	v_rcp_f32_e32 v139, v139
	v_ashrrev_i32_e32 v131, 31, v130
	v_lshlrev_b64 v[130:131], 10, v[130:131]
	v_lshl_add_u64 v[130:131], s[10:11], 0, v[130:131]
	v_lshl_add_u64 v[130:131], v[130:131], 0, s[8:9]
	v_pk_mul_f32 v[132:133], v[108:109], v[132:133]
	v_pk_mul_f32 v[134:135], v[110:111], v[134:135]
	v_pk_mul_f32 v[136:137], v[104:105], v[136:137]
	v_pk_mul_f32 v[138:139], v[106:107], v[138:139]
	v_lshl_add_u64 v[140:141], v[130:131], 0, v[152:153]
	v_cvt_pk_bf16_f32 v130, v132, v133
	v_cvt_pk_bf16_f32 v131, v134, v135
	v_cvt_pk_bf16_f32 v132, v136, v137
	v_cvt_pk_bf16_f32 v133, v138, v139
	flat_store_dwordx4 v[140:141], v[130:133] sc1
	v_mul_f32_e32 v134, 0xbfb8aa3b, v86
	v_mul_f32_e32 v135, 0xbfb8aa3b, v87
	v_mul_f32_e32 v132, 0xbfb8aa3b, v84
	v_mul_f32_e32 v133, 0xbfb8aa3b, v85
	v_mul_f32_e32 v136, 0xbfb8aa3b, v80
	v_mul_f32_e32 v137, 0xbfb8aa3b, v81
	v_mul_f32_e32 v138, 0xbfb8aa3b, v82
	v_mul_f32_e32 v139, 0xbfb8aa3b, v83
	v_exp_f32_e32 v132, v132
	v_exp_f32_e32 v133, v133
	v_exp_f32_e32 v134, v134
	v_exp_f32_e32 v135, v135
	v_exp_f32_e32 v136, v136
	v_exp_f32_e32 v137, v137
	v_exp_f32_e32 v138, v138
	v_exp_f32_e32 v139, v139
	v_add_f32_e32 v132, 1.0, v132
	v_add_f32_e32 v133, 1.0, v133
	v_add_f32_e32 v134, 1.0, v134
	v_add_f32_e32 v135, 1.0, v135
	v_add_f32_e32 v136, 1.0, v136
	v_add_f32_e32 v137, 1.0, v137
	v_add_f32_e32 v138, 1.0, v138
	v_add_f32_e32 v139, 1.0, v139
	v_or_b32_e32 v130, 32, v172
	v_rcp_f32_e32 v132, v132
	v_rcp_f32_e32 v133, v133
	v_rcp_f32_e32 v134, v134
	v_rcp_f32_e32 v135, v135
	v_rcp_f32_e32 v136, v136
	v_rcp_f32_e32 v137, v137
	v_rcp_f32_e32 v138, v138
	v_rcp_f32_e32 v139, v139
	v_ashrrev_i32_e32 v131, 31, v130
	v_lshlrev_b64 v[130:131], 10, v[130:131]
	v_lshl_add_u64 v[130:131], s[10:11], 0, v[130:131]
	v_lshl_add_u64 v[130:131], v[130:131], 0, s[8:9]
	v_pk_mul_f32 v[132:133], v[92:93], v[132:133]
	v_pk_mul_f32 v[134:135], v[94:95], v[134:135]
	v_pk_mul_f32 v[136:137], v[88:89], v[136:137]
	v_pk_mul_f32 v[138:139], v[90:91], v[138:139]
	v_lshl_add_u64 v[140:141], v[130:131], 0, v[152:153]
	v_cvt_pk_bf16_f32 v130, v132, v133
	v_cvt_pk_bf16_f32 v131, v134, v135
	v_cvt_pk_bf16_f32 v132, v136, v137
	v_cvt_pk_bf16_f32 v133, v138, v139
	v_mul_f32_e32 v134, 0xbfb8aa3b, v70
	v_mul_f32_e32 v135, 0xbfb8aa3b, v71
	flat_store_dwordx4 v[140:141], v[130:133] sc1
	v_exp_f32_e32 v134, v134
	v_exp_f32_e32 v135, v135
	v_mul_f32_e32 v132, 0xbfb8aa3b, v68
	v_mul_f32_e32 v133, 0xbfb8aa3b, v69
	v_mul_f32_e32 v136, 0xbfb8aa3b, v64
	v_mul_f32_e32 v137, 0xbfb8aa3b, v65
	v_mul_f32_e32 v138, 0xbfb8aa3b, v66
	v_mul_f32_e32 v139, 0xbfb8aa3b, v67
	v_exp_f32_e32 v132, v132
	v_exp_f32_e32 v133, v133
	v_exp_f32_e32 v136, v136
	v_exp_f32_e32 v137, v137
	v_exp_f32_e32 v138, v138
	v_exp_f32_e32 v139, v139
	v_add_f32_e32 v134, 1.0, v134
	v_add_f32_e32 v135, 1.0, v135
	v_or_b32_e32 v130, 48, v172
	v_add_f32_e32 v132, 1.0, v132
	v_add_f32_e32 v133, 1.0, v133
	v_rcp_f32_e32 v134, v134
	v_rcp_f32_e32 v135, v135
	v_add_f32_e32 v136, 1.0, v136
	v_add_f32_e32 v137, 1.0, v137
	v_add_f32_e32 v138, 1.0, v138
	v_add_f32_e32 v139, 1.0, v139
	v_ashrrev_i32_e32 v131, 31, v130
	v_rcp_f32_e32 v132, v132
	v_rcp_f32_e32 v133, v133
	v_rcp_f32_e32 v136, v136
	v_rcp_f32_e32 v137, v137
	v_rcp_f32_e32 v138, v138
	v_rcp_f32_e32 v139, v139
	v_lshlrev_b64 v[130:131], 10, v[130:131]
	v_lshl_add_u64 v[130:131], s[10:11], 0, v[130:131]
	v_lshl_add_u64 v[130:131], v[130:131], 0, s[8:9]
	v_pk_mul_f32 v[134:135], v[78:79], v[134:135]
	v_pk_mul_f32 v[132:133], v[76:77], v[132:133]
	v_pk_mul_f32 v[136:137], v[72:73], v[136:137]
	v_pk_mul_f32 v[138:139], v[74:75], v[138:139]
	v_lshl_add_u64 v[140:141], v[130:131], 0, v[152:153]
	v_cvt_pk_bf16_f32 v131, v134, v135
	v_mul_f32_e32 v134, 0xbfb8aa3b, v52
	v_mul_f32_e32 v135, 0xbfb8aa3b, v53
	v_cvt_pk_bf16_f32 v130, v132, v133
	v_cvt_pk_bf16_f32 v132, v136, v137
	v_cvt_pk_bf16_f32 v133, v138, v139
	v_exp_f32_e32 v134, v134
	v_exp_f32_e32 v135, v135
	flat_store_dwordx4 v[140:141], v[130:133] sc1
	v_mul_f32_e32 v136, 0xbfb8aa3b, v50
	v_mul_f32_e32 v137, 0xbfb8aa3b, v51
	v_mul_f32_e32 v132, 0xbfb8aa3b, v54
	v_mul_f32_e32 v133, 0xbfb8aa3b, v55
	v_exp_f32_e32 v132, v132
	v_exp_f32_e32 v133, v133
	v_exp_f32_e32 v136, v136
	v_exp_f32_e32 v137, v137
	v_add_f32_e32 v130, 1.0, v134
	v_add_f32_e32 v131, 1.0, v135
	v_mul_f32_e32 v134, 0xbfb8aa3b, v48
	v_mul_f32_e32 v135, 0xbfb8aa3b, v49
	v_exp_f32_e32 v134, v134
	v_exp_f32_e32 v135, v135
	v_add_f32_e32 v132, 1.0, v132
	v_add_f32_e32 v133, 1.0, v133
	v_add_f32_e32 v136, 1.0, v136
	v_add_f32_e32 v137, 1.0, v137
	v_rcp_f32_e32 v130, v130
	v_rcp_f32_e32 v131, v131
	v_rcp_f32_e32 v132, v132
	v_rcp_f32_e32 v133, v133
	v_rcp_f32_e32 v136, v136
	v_rcp_f32_e32 v137, v137
	v_add_f32_e32 v134, 1.0, v134
	v_add_f32_e32 v135, 1.0, v135
	v_rcp_f32_e32 v134, v134
	v_rcp_f32_e32 v135, v135
	v_pk_mul_f32 v[130:131], v[60:61], v[130:131]
	v_pk_mul_f32 v[132:133], v[62:63], v[132:133]
	v_pk_mul_f32 v[136:137], v[58:59], v[136:137]
	v_cvt_pk_bf16_f32 v130, v130, v131
	v_cvt_pk_bf16_f32 v131, v132, v133
	v_cvt_pk_bf16_f32 v133, v136, v137
	v_mul_f32_e32 v136, 0xbfb8aa3b, v36
	v_mul_f32_e32 v137, 0xbfb8aa3b, v37
	v_exp_f32_e32 v136, v136
	v_exp_f32_e32 v137, v137
	v_pk_mul_f32 v[134:135], v[56:57], v[134:135]
	s_mov_b32 s2, 0x20000
	v_cvt_pk_bf16_f32 v132, v134, v135
	v_add_co_u32_e32 v134, vcc, s2, v128
	s_mov_b32 s2, 0x24000
	s_nop 0
	v_addc_co_u32_e32 v135, vcc, 0, v129, vcc
	flat_store_dwordx4 v[134:135], v[130:133] sc1
	v_mul_f32_e32 v134, 0xbfb8aa3b, v32
	v_mul_f32_e32 v135, 0xbfb8aa3b, v33
	v_add_f32_e32 v130, 1.0, v136
	v_add_f32_e32 v131, 1.0, v137
	v_mul_f32_e32 v132, 0xbfb8aa3b, v38
	v_mul_f32_e32 v133, 0xbfb8aa3b, v39
	v_mul_f32_e32 v136, 0xbfb8aa3b, v34
	v_mul_f32_e32 v137, 0xbfb8aa3b, v35
	v_exp_f32_e32 v132, v132
	v_exp_f32_e32 v133, v133
	v_exp_f32_e32 v136, v136
	v_exp_f32_e32 v137, v137
	v_exp_f32_e32 v134, v134
	v_exp_f32_e32 v135, v135
	v_add_f32_e32 v132, 1.0, v132
	v_add_f32_e32 v133, 1.0, v133
	v_add_f32_e32 v136, 1.0, v136
	v_add_f32_e32 v137, 1.0, v137
	v_rcp_f32_e32 v130, v130
	v_rcp_f32_e32 v131, v131
	v_rcp_f32_e32 v132, v132
	v_rcp_f32_e32 v133, v133
	v_rcp_f32_e32 v136, v136
	v_rcp_f32_e32 v137, v137
	v_add_f32_e32 v134, 1.0, v134
	v_add_f32_e32 v135, 1.0, v135
	v_rcp_f32_e32 v134, v134
	v_rcp_f32_e32 v135, v135
	v_pk_mul_f32 v[130:131], v[44:45], v[130:131]
	v_pk_mul_f32 v[132:133], v[46:47], v[132:133]
	v_pk_mul_f32 v[136:137], v[42:43], v[136:137]
	v_cvt_pk_bf16_f32 v130, v130, v131
	v_cvt_pk_bf16_f32 v131, v132, v133
	v_cvt_pk_bf16_f32 v133, v136, v137
	v_mul_f32_e32 v136, 0xbfb8aa3b, v20
	v_mul_f32_e32 v137, 0xbfb8aa3b, v21
	v_exp_f32_e32 v136, v136
	v_exp_f32_e32 v137, v137
	v_pk_mul_f32 v[134:135], v[40:41], v[134:135]
	s_nop 0
	v_cvt_pk_bf16_f32 v132, v134, v135
	v_add_co_u32_e32 v134, vcc, s2, v128
	s_mov_b32 s2, 0x28000
	s_nop 0
	v_addc_co_u32_e32 v135, vcc, 0, v129, vcc
	flat_store_dwordx4 v[134:135], v[130:133] sc1
	v_mul_f32_e32 v134, 0xbfb8aa3b, v16
	v_mul_f32_e32 v135, 0xbfb8aa3b, v17
	v_add_f32_e32 v130, 1.0, v136
	v_add_f32_e32 v131, 1.0, v137
	v_mul_f32_e32 v132, 0xbfb8aa3b, v22
	v_mul_f32_e32 v133, 0xbfb8aa3b, v23
	v_mul_f32_e32 v136, 0xbfb8aa3b, v18
	v_mul_f32_e32 v137, 0xbfb8aa3b, v19
	v_exp_f32_e32 v132, v132
	v_exp_f32_e32 v133, v133
	v_exp_f32_e32 v136, v136
	v_exp_f32_e32 v137, v137
	v_exp_f32_e32 v134, v134
	v_exp_f32_e32 v135, v135
	v_add_f32_e32 v132, 1.0, v132
	v_add_f32_e32 v133, 1.0, v133
	v_add_f32_e32 v136, 1.0, v136
	v_add_f32_e32 v137, 1.0, v137
	v_rcp_f32_e32 v130, v130
	v_rcp_f32_e32 v131, v131
	v_rcp_f32_e32 v132, v132
	v_rcp_f32_e32 v133, v133
	v_rcp_f32_e32 v136, v136
	v_rcp_f32_e32 v137, v137
	v_add_f32_e32 v134, 1.0, v134
	v_add_f32_e32 v135, 1.0, v135
	v_rcp_f32_e32 v134, v134
	v_rcp_f32_e32 v135, v135
	v_pk_mul_f32 v[130:131], v[28:29], v[130:131]
	v_pk_mul_f32 v[132:133], v[30:31], v[132:133]
	v_pk_mul_f32 v[136:137], v[26:27], v[136:137]
	v_cvt_pk_bf16_f32 v130, v130, v131
	v_cvt_pk_bf16_f32 v131, v132, v133
	v_cvt_pk_bf16_f32 v133, v136, v137
	v_mul_f32_e32 v136, 0xbfb8aa3b, v4
	v_mul_f32_e32 v137, 0xbfb8aa3b, v5
	v_exp_f32_e32 v136, v136
	v_exp_f32_e32 v137, v137
	v_pk_mul_f32 v[134:135], v[24:25], v[134:135]
	s_nop 0
	v_cvt_pk_bf16_f32 v132, v134, v135
	v_add_co_u32_e32 v134, vcc, s2, v128
	s_nop 1
	v_addc_co_u32_e32 v135, vcc, 0, v129, vcc
	flat_store_dwordx4 v[134:135], v[130:133] sc1
	v_mul_f32_e32 v134, 0xbfb8aa3b, v0
	v_mul_f32_e32 v135, 0xbfb8aa3b, v1
	v_add_f32_e32 v130, 1.0, v136
	v_add_f32_e32 v131, 1.0, v137
	v_mul_f32_e32 v132, 0xbfb8aa3b, v6
	v_mul_f32_e32 v133, 0xbfb8aa3b, v7
	v_mul_f32_e32 v136, 0xbfb8aa3b, v2
	v_mul_f32_e32 v137, 0xbfb8aa3b, v3
	v_exp_f32_e32 v132, v132
	v_exp_f32_e32 v133, v133
	v_exp_f32_e32 v134, v134
	v_exp_f32_e32 v135, v135
	v_exp_f32_e32 v136, v136
	v_exp_f32_e32 v137, v137
	v_add_f32_e32 v132, 1.0, v132
	v_add_f32_e32 v133, 1.0, v133
	v_add_f32_e32 v134, 1.0, v134
	v_add_f32_e32 v135, 1.0, v135
	v_add_f32_e32 v136, 1.0, v136
	v_add_f32_e32 v137, 1.0, v137
	v_rcp_f32_e32 v130, v130
	v_rcp_f32_e32 v131, v131
	v_rcp_f32_e32 v132, v132
	v_rcp_f32_e32 v133, v133
	v_rcp_f32_e32 v134, v134
	v_rcp_f32_e32 v135, v135
	v_rcp_f32_e32 v136, v136
	v_rcp_f32_e32 v137, v137
	v_pk_mul_f32 v[130:131], v[12:13], v[130:131]
	v_pk_mul_f32 v[132:133], v[14:15], v[132:133]
	v_pk_mul_f32 v[134:135], v[8:9], v[134:135]
	v_pk_mul_f32 v[136:137], v[10:11], v[136:137]
	v_add_co_u32_e32 v128, vcc, 0x2c000, v128
	v_cvt_pk_bf16_f32 v130, v130, v131
	v_cvt_pk_bf16_f32 v131, v132, v133
	v_cvt_pk_bf16_f32 v132, v134, v135
	v_cvt_pk_bf16_f32 v133, v136, v137
	v_addc_co_u32_e32 v129, vcc, 0, v129, vcc
	flat_store_dwordx4 v[128:129], v[130:133] sc1

.LBB0_1133:
	s_andn2_b64 vcc, exec, s[8:9]
	s_cbranch_vccnz .LBB0_1135
	s_mov_b32 s89, s3
	s_lshl_b64 s[8:9], s[88:89], 24
	s_add_u32 s8, s56, s8
	v_ashrrev_i32_e32 v173, 31, v172
	s_addc_u32 s9, s57, s9
	s_lshl_b32 s10, s14, 8
	v_lshlrev_b64 v[128:129], 11, v[172:173]
	s_ashr_i32 s11, s10, 31
	v_lshl_add_u64 v[128:129], s[8:9], 0, v[128:129]
	s_lshl_b64 s[10:11], s[10:11], 1
	v_lshl_add_u64 v[128:129], v[128:129], 0, s[10:11]
	v_lshlrev_b32_e32 v152, 1, v186
	v_lshl_add_u64 v[132:133], v[128:129], 0, v[152:153]
	v_cvt_pk_bf16_f32 v128, v124, v125
	v_cvt_pk_bf16_f32 v129, v126, v127
	v_cvt_pk_bf16_f32 v130, v120, v121
	v_cvt_pk_bf16_f32 v131, v122, v123
	flat_store_dwordx4 v[132:133], v[128:131] sc1
	s_mov_b32 s2, 0x40000
	s_waitcnt lgkmcnt(0)
	v_add_co_u32_e32 v136, vcc, s2, v132
	v_cvt_pk_bf16_f32 v128, v116, v117
	v_cvt_pk_bf16_f32 v129, v118, v119
	v_cvt_pk_bf16_f32 v130, v112, v113
	v_cvt_pk_bf16_f32 v131, v114, v115
	flat_store_dwordx4 v[132:133], v[128:131] offset:256 sc1
	v_addc_co_u32_e32 v137, vcc, 0, v133, vcc
	s_nop 0
	v_or_b32_e32 v128, 16, v172
	v_ashrrev_i32_e32 v129, 31, v128
	v_lshlrev_b64 v[128:129], 11, v[128:129]
	v_lshl_add_u64 v[128:129], s[8:9], 0, v[128:129]
	v_lshl_add_u64 v[128:129], v[128:129], 0, s[10:11]
	v_lshl_add_u64 v[134:135], v[128:129], 0, v[152:153]
	v_cvt_pk_bf16_f32 v128, v108, v109
	v_cvt_pk_bf16_f32 v129, v110, v111
	v_cvt_pk_bf16_f32 v130, v104, v105
	v_cvt_pk_bf16_f32 v131, v106, v107
	flat_store_dwordx4 v[134:135], v[128:131] sc1
	s_mov_b32 s2, 0x48000
	s_nop 0
	v_cvt_pk_bf16_f32 v128, v100, v101
	v_cvt_pk_bf16_f32 v129, v102, v103
	v_cvt_pk_bf16_f32 v130, v96, v97
	v_cvt_pk_bf16_f32 v131, v98, v99
	flat_store_dwordx4 v[134:135], v[128:131] offset:256 sc1
	s_nop 1
	v_or_b32_e32 v128, 32, v172
	v_ashrrev_i32_e32 v129, 31, v128
	v_lshlrev_b64 v[128:129], 11, v[128:129]
	v_lshl_add_u64 v[128:129], s[8:9], 0, v[128:129]
	v_lshl_add_u64 v[128:129], v[128:129], 0, s[10:11]
	v_lshl_add_u64 v[134:135], v[128:129], 0, v[152:153]
	v_cvt_pk_bf16_f32 v128, v92, v93
	v_cvt_pk_bf16_f32 v129, v94, v95
	v_cvt_pk_bf16_f32 v130, v88, v89
	v_cvt_pk_bf16_f32 v131, v90, v91
	flat_store_dwordx4 v[134:135], v[128:131] sc1
	s_nop 1
	v_cvt_pk_bf16_f32 v128, v84, v85
	v_cvt_pk_bf16_f32 v129, v86, v87
	v_cvt_pk_bf16_f32 v130, v80, v81
	v_cvt_pk_bf16_f32 v131, v82, v83
	flat_store_dwordx4 v[134:135], v[128:131] offset:256 sc1
	s_nop 1
	v_or_b32_e32 v128, 48, v172
	v_ashrrev_i32_e32 v129, 31, v128
	v_lshlrev_b64 v[128:129], 11, v[128:129]
	v_lshl_add_u64 v[128:129], s[8:9], 0, v[128:129]
	v_lshl_add_u64 v[128:129], v[128:129], 0, s[10:11]
	v_lshl_add_u64 v[134:135], v[128:129], 0, v[152:153]
	v_cvt_pk_bf16_f32 v128, v76, v77
	v_cvt_pk_bf16_f32 v129, v78, v79
	v_cvt_pk_bf16_f32 v130, v72, v73
	v_cvt_pk_bf16_f32 v131, v74, v75
	flat_store_dwordx4 v[134:135], v[128:131] sc1
	s_mov_b64 s[8:9], 0x40000
	s_nop 0
	v_cvt_pk_bf16_f32 v128, v68, v69
	v_cvt_pk_bf16_f32 v129, v70, v71
	v_cvt_pk_bf16_f32 v130, v64, v65
	v_cvt_pk_bf16_f32 v131, v66, v67
	flat_store_dwordx4 v[134:135], v[128:131] offset:256 sc1
	v_lshl_add_u64 v[134:135], v[132:133], 0, s[8:9]
	s_mov_b64 s[8:9], 0x48000
	v_cvt_pk_bf16_f32 v128, v60, v61
	v_cvt_pk_bf16_f32 v129, v62, v63
	v_cvt_pk_bf16_f32 v130, v56, v57
	v_cvt_pk_bf16_f32 v131, v58, v59
	flat_store_dwordx4 v[136:137], v[128:131] sc1
	v_add_co_u32_e32 v136, vcc, s2, v132
	s_nop 0
	v_cvt_pk_bf16_f32 v128, v52, v53
	v_cvt_pk_bf16_f32 v129, v54, v55
	v_cvt_pk_bf16_f32 v130, v48, v49
	v_cvt_pk_bf16_f32 v131, v50, v51
	flat_store_dwordx4 v[134:135], v[128:131] offset:256 sc1
	v_addc_co_u32_e32 v137, vcc, 0, v133, vcc
	s_nop 0
	v_cvt_pk_bf16_f32 v128, v44, v45
	v_cvt_pk_bf16_f32 v129, v46, v47
	v_cvt_pk_bf16_f32 v130, v40, v41
	v_cvt_pk_bf16_f32 v131, v42, v43
	s_mov_b32 s2, 0x50000
	v_lshl_add_u64 v[134:135], v[132:133], 0, s[8:9]
	flat_store_dwordx4 v[136:137], v[128:131] sc1
	v_add_co_u32_e32 v136, vcc, s2, v132
	s_nop 0
	v_cvt_pk_bf16_f32 v128, v36, v37
	v_cvt_pk_bf16_f32 v129, v38, v39
	v_cvt_pk_bf16_f32 v130, v32, v33
	v_cvt_pk_bf16_f32 v131, v34, v35
	flat_store_dwordx4 v[134:135], v[128:131] offset:256 sc1
	s_mov_b64 s[8:9], 0x50000
	v_addc_co_u32_e32 v137, vcc, 0, v133, vcc
	v_cvt_pk_bf16_f32 v128, v28, v29
	v_cvt_pk_bf16_f32 v129, v30, v31
	v_cvt_pk_bf16_f32 v130, v24, v25
	v_cvt_pk_bf16_f32 v131, v26, v27
	v_lshl_add_u64 v[134:135], v[132:133], 0, s[8:9]
	flat_store_dwordx4 v[136:137], v[128:131] sc1
	s_mov_b64 s[8:9], 0x58000
	s_mov_b32 s2, 0x58000
	v_cvt_pk_bf16_f32 v128, v20, v21
	v_cvt_pk_bf16_f32 v129, v22, v23
	v_cvt_pk_bf16_f32 v130, v16, v17
	v_cvt_pk_bf16_f32 v131, v18, v19
	flat_store_dwordx4 v[134:135], v[128:131] offset:256 sc1
	v_lshl_add_u64 v[134:135], v[132:133], 0, s[8:9]
	v_add_co_u32_e32 v132, vcc, s2, v132
	v_cvt_pk_bf16_f32 v128, v12, v13
	v_cvt_pk_bf16_f32 v129, v14, v15
	v_cvt_pk_bf16_f32 v130, v8, v9
	v_cvt_pk_bf16_f32 v131, v10, v11
	v_addc_co_u32_e32 v133, vcc, 0, v133, vcc
	flat_store_dwordx4 v[132:133], v[128:131] sc1
	s_nop 1
	v_cvt_pk_bf16_f32 v128, v4, v5
	v_cvt_pk_bf16_f32 v129, v6, v7
	v_cvt_pk_bf16_f32 v130, v0, v1
	v_cvt_pk_bf16_f32 v131, v2, v3
	flat_store_dwordx4 v[134:135], v[128:131] offset:256 sc1

.LBB0_1136:
	s_andn2_b64 vcc, exec, s[8:9]
	s_cbranch_vccnz .LBB0_535
	s_cmp_eq_u32 s93, 0
	s_cbranch_scc0 .LBB0_535
	v_mul_f32_e32 v132, 0xbfb8aa3b, v124
	v_mul_f32_e32 v133, 0xbfb8aa3b, v125
	v_exp_f32_e32 v132, v132
	v_exp_f32_e32 v133, v133
	v_mov_b64_e32 v[128:129], s[58:59]
	s_movk_i32 s2, 0x1600
	v_add_f32_e32 v132, 1.0, v132
	v_add_f32_e32 v133, 1.0, v133
	v_rcp_f32_e32 v132, v132
	v_rcp_f32_e32 v133, v133
	v_mad_i64_i32 v[130:131], s[8:9], v172, s2, v[128:129]
	s_lshl_b32 s8, s14, 7
	v_pk_mul_f32 v[124:125], v[124:125], v[132:133]
	v_mul_f32_e32 v132, 0xbfb8aa3b, v126
	v_mul_f32_e32 v133, 0xbfb8aa3b, v127
	v_exp_f32_e32 v132, v132
	v_exp_f32_e32 v133, v133
	v_pk_mul_f32 v[116:117], v[124:125], v[116:117]
	s_ashr_i32 s9, s8, 31
	v_add_f32_e32 v124, 1.0, v132
	v_add_f32_e32 v125, 1.0, v133
	v_mul_f32_e32 v132, 0xbfb8aa3b, v120
	v_mul_f32_e32 v133, 0xbfb8aa3b, v121
	v_rcp_f32_e32 v124, v124
	v_rcp_f32_e32 v125, v125
	v_exp_f32_e32 v132, v132
	v_exp_f32_e32 v133, v133
	s_lshl_b64 s[8:9], s[8:9], 1
	v_pk_mul_f32 v[124:125], v[126:127], v[124:125]
	v_add_f32_e32 v126, 1.0, v132
	v_add_f32_e32 v127, 1.0, v133
	v_mul_f32_e32 v132, 0xbfb8aa3b, v122
	v_mul_f32_e32 v133, 0xbfb8aa3b, v123
	v_exp_f32_e32 v132, v132
	v_exp_f32_e32 v133, v133
	v_rcp_f32_e32 v126, v126
	v_rcp_f32_e32 v127, v127
	v_add_f32_e32 v132, 1.0, v132
	v_add_f32_e32 v133, 1.0, v133
	v_rcp_f32_e32 v132, v132
	v_rcp_f32_e32 v133, v133
	v_pk_mul_f32 v[120:121], v[120:121], v[126:127]
	v_lshl_add_u64 v[130:131], v[130:131], 0, s[8:9]
	v_pk_mul_f32 v[120:121], v[120:121], v[112:113]
	v_pk_mul_f32 v[112:113], v[122:123], v[132:133]
	v_pk_mul_f32 v[118:119], v[124:125], v[118:119]
	v_pk_mul_f32 v[122:123], v[112:113], v[114:115]
	v_lshlrev_b32_e32 v152, 1, v186
	v_lshl_add_u64 v[124:125], v[130:131], 0, v[152:153]
	v_cvt_pk_bf16_f32 v112, v116, v117
	v_cvt_pk_bf16_f32 v113, v118, v119
	v_cvt_pk_bf16_f32 v114, v120, v121
	v_cvt_pk_bf16_f32 v115, v122, v123
	flat_store_dwordx4 v[124:125], v[112:115] sc1
	s_nop 1
	v_mul_f32_e32 v112, 0xbfb8aa3b, v108
	v_mul_f32_e32 v113, 0xbfb8aa3b, v109
	v_exp_f32_e32 v112, v112
	v_exp_f32_e32 v113, v113
	v_or_b32_e32 v114, 16, v172
	v_mad_i64_i32 v[114:115], s[10:11], v114, s2, v[128:129]
	v_add_f32_e32 v112, 1.0, v112
	v_add_f32_e32 v113, 1.0, v113
	v_rcp_f32_e32 v112, v112
	v_rcp_f32_e32 v113, v113
	v_lshl_add_u64 v[114:115], v[114:115], 0, s[8:9]
	v_pk_mul_f32 v[108:109], v[108:109], v[112:113]
	v_mul_f32_e32 v112, 0xbfb8aa3b, v110
	v_mul_f32_e32 v113, 0xbfb8aa3b, v111
	v_exp_f32_e32 v112, v112
	v_exp_f32_e32 v113, v113
	v_pk_mul_f32 v[100:101], v[108:109], v[100:101]
	v_add_f32_e32 v108, 1.0, v112
	v_add_f32_e32 v109, 1.0, v113
	v_mul_f32_e32 v112, 0xbfb8aa3b, v104
	v_mul_f32_e32 v113, 0xbfb8aa3b, v105
	v_rcp_f32_e32 v108, v108
	v_rcp_f32_e32 v109, v109
	v_exp_f32_e32 v112, v112
	v_exp_f32_e32 v113, v113
	v_pk_mul_f32 v[108:109], v[110:111], v[108:109]
	v_add_f32_e32 v110, 1.0, v112
	v_add_f32_e32 v111, 1.0, v113
	v_mul_f32_e32 v112, 0xbfb8aa3b, v106
	v_mul_f32_e32 v113, 0xbfb8aa3b, v107
	v_exp_f32_e32 v112, v112
	v_exp_f32_e32 v113, v113
	v_rcp_f32_e32 v110, v110
	v_rcp_f32_e32 v111, v111
	v_add_f32_e32 v112, 1.0, v112
	v_add_f32_e32 v113, 1.0, v113
	v_rcp_f32_e32 v112, v112
	v_rcp_f32_e32 v113, v113
	v_pk_mul_f32 v[104:105], v[104:105], v[110:111]
	v_pk_mul_f32 v[102:103], v[108:109], v[102:103]
	v_pk_mul_f32 v[104:105], v[104:105], v[96:97]
	v_pk_mul_f32 v[96:97], v[106:107], v[112:113]
	v_lshl_add_u64 v[108:109], v[114:115], 0, v[152:153]
	v_pk_mul_f32 v[106:107], v[96:97], v[98:99]
	v_cvt_pk_bf16_f32 v96, v100, v101
	v_cvt_pk_bf16_f32 v97, v102, v103
	v_cvt_pk_bf16_f32 v98, v104, v105
	v_cvt_pk_bf16_f32 v99, v106, v107
	flat_store_dwordx4 v[108:109], v[96:99] sc1
	s_nop 1
	v_mul_f32_e32 v96, 0xbfb8aa3b, v92
	v_mul_f32_e32 v97, 0xbfb8aa3b, v93
	v_exp_f32_e32 v96, v96
	v_exp_f32_e32 v97, v97
	v_or_b32_e32 v98, 32, v172
	v_mad_i64_i32 v[98:99], s[10:11], v98, s2, v[128:129]
	v_add_f32_e32 v96, 1.0, v96
	v_add_f32_e32 v97, 1.0, v97
	v_rcp_f32_e32 v96, v96
	v_rcp_f32_e32 v97, v97
	v_lshl_add_u64 v[98:99], v[98:99], 0, s[8:9]
	v_pk_mul_f32 v[92:93], v[92:93], v[96:97]
	v_mul_f32_e32 v96, 0xbfb8aa3b, v94
	v_mul_f32_e32 v97, 0xbfb8aa3b, v95
	v_exp_f32_e32 v96, v96
	v_exp_f32_e32 v97, v97
	v_pk_mul_f32 v[84:85], v[92:93], v[84:85]
	v_add_f32_e32 v92, 1.0, v96
	v_add_f32_e32 v93, 1.0, v97
	v_mul_f32_e32 v96, 0xbfb8aa3b, v88
	v_mul_f32_e32 v97, 0xbfb8aa3b, v89
	v_rcp_f32_e32 v92, v92
	v_rcp_f32_e32 v93, v93
	v_exp_f32_e32 v96, v96
	v_exp_f32_e32 v97, v97
	v_pk_mul_f32 v[92:93], v[94:95], v[92:93]
	v_add_f32_e32 v94, 1.0, v96
	v_add_f32_e32 v95, 1.0, v97
	v_mul_f32_e32 v96, 0xbfb8aa3b, v90
	v_mul_f32_e32 v97, 0xbfb8aa3b, v91
	v_exp_f32_e32 v96, v96
	v_exp_f32_e32 v97, v97
	v_rcp_f32_e32 v94, v94
	v_rcp_f32_e32 v95, v95
	v_add_f32_e32 v96, 1.0, v96
	v_add_f32_e32 v97, 1.0, v97
	v_rcp_f32_e32 v96, v96
	v_rcp_f32_e32 v97, v97
	v_pk_mul_f32 v[88:89], v[88:89], v[94:95]
	v_pk_mul_f32 v[86:87], v[92:93], v[86:87]
	v_pk_mul_f32 v[88:89], v[88:89], v[80:81]
	v_pk_mul_f32 v[80:81], v[90:91], v[96:97]
	v_lshl_add_u64 v[92:93], v[98:99], 0, v[152:153]
	v_pk_mul_f32 v[90:91], v[80:81], v[82:83]
	v_cvt_pk_bf16_f32 v80, v84, v85
	v_cvt_pk_bf16_f32 v81, v86, v87
	v_cvt_pk_bf16_f32 v82, v88, v89
	v_cvt_pk_bf16_f32 v83, v90, v91
	flat_store_dwordx4 v[92:93], v[80:83] sc1
	s_nop 1
	v_mul_f32_e32 v80, 0xbfb8aa3b, v76
	v_mul_f32_e32 v81, 0xbfb8aa3b, v77
	v_exp_f32_e32 v80, v80
	v_exp_f32_e32 v81, v81
	v_or_b32_e32 v82, 48, v172
	v_mad_i64_i32 v[82:83], s[10:11], v82, s2, v[128:129]
	v_add_f32_e32 v80, 1.0, v80
	v_add_f32_e32 v81, 1.0, v81
	v_rcp_f32_e32 v80, v80
	v_rcp_f32_e32 v81, v81
	v_lshl_add_u64 v[82:83], v[82:83], 0, s[8:9]
	v_pk_mul_f32 v[76:77], v[76:77], v[80:81]
	v_mul_f32_e32 v80, 0xbfb8aa3b, v78
	v_mul_f32_e32 v81, 0xbfb8aa3b, v79
	v_exp_f32_e32 v80, v80
	v_exp_f32_e32 v81, v81
	v_pk_mul_f32 v[68:69], v[76:77], v[68:69]
	v_add_f32_e32 v76, 1.0, v80
	v_add_f32_e32 v77, 1.0, v81
	v_mul_f32_e32 v80, 0xbfb8aa3b, v72
	v_mul_f32_e32 v81, 0xbfb8aa3b, v73
	v_rcp_f32_e32 v76, v76
	v_rcp_f32_e32 v77, v77
	v_exp_f32_e32 v80, v80
	v_exp_f32_e32 v81, v81
	v_pk_mul_f32 v[76:77], v[78:79], v[76:77]
	v_add_f32_e32 v78, 1.0, v80
	v_add_f32_e32 v79, 1.0, v81
	v_mul_f32_e32 v80, 0xbfb8aa3b, v74
	v_mul_f32_e32 v81, 0xbfb8aa3b, v75
	v_exp_f32_e32 v80, v80
	v_exp_f32_e32 v81, v81
	v_rcp_f32_e32 v78, v78
	v_rcp_f32_e32 v79, v79
	v_add_f32_e32 v80, 1.0, v80
	v_add_f32_e32 v81, 1.0, v81
	v_rcp_f32_e32 v80, v80
	v_rcp_f32_e32 v81, v81
	v_pk_mul_f32 v[72:73], v[72:73], v[78:79]
	v_pk_mul_f32 v[70:71], v[76:77], v[70:71]
	v_pk_mul_f32 v[72:73], v[72:73], v[64:65]
	v_pk_mul_f32 v[64:65], v[74:75], v[80:81]
	v_lshl_add_u64 v[76:77], v[82:83], 0, v[152:153]
	v_pk_mul_f32 v[74:75], v[64:65], v[66:67]
	v_cvt_pk_bf16_f32 v64, v68, v69
	v_cvt_pk_bf16_f32 v65, v70, v71
	v_cvt_pk_bf16_f32 v66, v72, v73
	v_cvt_pk_bf16_f32 v67, v74, v75
	flat_store_dwordx4 v[76:77], v[64:67] sc1
	s_nop 1
	v_mul_f32_e32 v64, 0xbfb8aa3b, v60
	v_mul_f32_e32 v65, 0xbfb8aa3b, v61
	v_exp_f32_e32 v64, v64
	v_exp_f32_e32 v65, v65
	v_add_u32_e32 v66, 0x80, v172
	v_mad_i64_i32 v[66:67], s[10:11], v66, s2, v[128:129]
	v_add_f32_e32 v64, 1.0, v64
	v_add_f32_e32 v65, 1.0, v65
	v_rcp_f32_e32 v64, v64
	v_rcp_f32_e32 v65, v65
	v_lshl_add_u64 v[66:67], v[66:67], 0, s[8:9]
	v_pk_mul_f32 v[60:61], v[60:61], v[64:65]
	v_mul_f32_e32 v64, 0xbfb8aa3b, v62
	v_mul_f32_e32 v65, 0xbfb8aa3b, v63
	v_exp_f32_e32 v64, v64
	v_exp_f32_e32 v65, v65
	v_pk_mul_f32 v[52:53], v[60:61], v[52:53]
	v_add_f32_e32 v60, 1.0, v64
	v_add_f32_e32 v61, 1.0, v65
	v_mul_f32_e32 v64, 0xbfb8aa3b, v56
	v_mul_f32_e32 v65, 0xbfb8aa3b, v57
	v_rcp_f32_e32 v60, v60
	v_rcp_f32_e32 v61, v61
	v_exp_f32_e32 v64, v64
	v_exp_f32_e32 v65, v65
	v_pk_mul_f32 v[60:61], v[62:63], v[60:61]
	v_add_f32_e32 v62, 1.0, v64
	v_add_f32_e32 v63, 1.0, v65
	v_mul_f32_e32 v64, 0xbfb8aa3b, v58
	v_mul_f32_e32 v65, 0xbfb8aa3b, v59
	v_exp_f32_e32 v64, v64
	v_exp_f32_e32 v65, v65
	v_rcp_f32_e32 v62, v62
	v_rcp_f32_e32 v63, v63
	v_add_f32_e32 v64, 1.0, v64
	v_add_f32_e32 v65, 1.0, v65
	v_rcp_f32_e32 v64, v64
	v_rcp_f32_e32 v65, v65
	v_pk_mul_f32 v[56:57], v[56:57], v[62:63]
	v_pk_mul_f32 v[54:55], v[60:61], v[54:55]
	v_pk_mul_f32 v[56:57], v[56:57], v[48:49]
	v_pk_mul_f32 v[48:49], v[58:59], v[64:65]
	v_lshl_add_u64 v[60:61], v[66:67], 0, v[152:153]
	v_pk_mul_f32 v[58:59], v[48:49], v[50:51]
	v_cvt_pk_bf16_f32 v48, v52, v53
	v_cvt_pk_bf16_f32 v49, v54, v55
	v_cvt_pk_bf16_f32 v50, v56, v57
	v_cvt_pk_bf16_f32 v51, v58, v59
	flat_store_dwordx4 v[60:61], v[48:51] sc1
	s_nop 1
	v_mul_f32_e32 v48, 0xbfb8aa3b, v44
	v_mul_f32_e32 v49, 0xbfb8aa3b, v45
	v_exp_f32_e32 v48, v48
	v_exp_f32_e32 v49, v49
	v_add_u32_e32 v50, 0x90, v172
	v_mad_i64_i32 v[50:51], s[10:11], v50, s2, v[128:129]
	v_add_f32_e32 v48, 1.0, v48
	v_add_f32_e32 v49, 1.0, v49
	v_rcp_f32_e32 v48, v48
	v_rcp_f32_e32 v49, v49
	v_lshl_add_u64 v[50:51], v[50:51], 0, s[8:9]
	v_pk_mul_f32 v[44:45], v[44:45], v[48:49]
	v_mul_f32_e32 v48, 0xbfb8aa3b, v46
	v_mul_f32_e32 v49, 0xbfb8aa3b, v47
	v_exp_f32_e32 v48, v48
	v_exp_f32_e32 v49, v49
	v_pk_mul_f32 v[36:37], v[44:45], v[36:37]
	v_add_f32_e32 v44, 1.0, v48
	v_add_f32_e32 v45, 1.0, v49
	v_mul_f32_e32 v48, 0xbfb8aa3b, v40
	v_mul_f32_e32 v49, 0xbfb8aa3b, v41
	v_rcp_f32_e32 v44, v44
	v_rcp_f32_e32 v45, v45
	v_exp_f32_e32 v48, v48
	v_exp_f32_e32 v49, v49
	v_pk_mul_f32 v[44:45], v[46:47], v[44:45]
	v_add_f32_e32 v46, 1.0, v48
	v_add_f32_e32 v47, 1.0, v49
	v_mul_f32_e32 v48, 0xbfb8aa3b, v42
	v_mul_f32_e32 v49, 0xbfb8aa3b, v43
	v_exp_f32_e32 v48, v48
	v_exp_f32_e32 v49, v49
	v_rcp_f32_e32 v46, v46
	v_rcp_f32_e32 v47, v47
	v_add_f32_e32 v48, 1.0, v48
	v_add_f32_e32 v49, 1.0, v49
	v_rcp_f32_e32 v48, v48
	v_rcp_f32_e32 v49, v49
	v_pk_mul_f32 v[40:41], v[40:41], v[46:47]
	v_pk_mul_f32 v[38:39], v[44:45], v[38:39]
	v_pk_mul_f32 v[40:41], v[40:41], v[32:33]
	v_pk_mul_f32 v[32:33], v[42:43], v[48:49]
	v_lshl_add_u64 v[44:45], v[50:51], 0, v[152:153]
	v_pk_mul_f32 v[42:43], v[32:33], v[34:35]
	v_cvt_pk_bf16_f32 v32, v36, v37
	v_cvt_pk_bf16_f32 v33, v38, v39
	v_cvt_pk_bf16_f32 v34, v40, v41
	v_cvt_pk_bf16_f32 v35, v42, v43
	flat_store_dwordx4 v[44:45], v[32:35] sc1
	s_nop 1
	v_mul_f32_e32 v32, 0xbfb8aa3b, v28
	v_mul_f32_e32 v33, 0xbfb8aa3b, v29
	v_exp_f32_e32 v32, v32
	v_exp_f32_e32 v33, v33
	v_add_u32_e32 v34, 0xa0, v172
	v_mad_i64_i32 v[34:35], s[10:11], v34, s2, v[128:129]
	v_add_f32_e32 v32, 1.0, v32
	v_add_f32_e32 v33, 1.0, v33
	v_rcp_f32_e32 v32, v32
	v_rcp_f32_e32 v33, v33
	v_lshl_add_u64 v[34:35], v[34:35], 0, s[8:9]
	v_pk_mul_f32 v[28:29], v[28:29], v[32:33]
	v_mul_f32_e32 v32, 0xbfb8aa3b, v30
	v_mul_f32_e32 v33, 0xbfb8aa3b, v31
	v_exp_f32_e32 v32, v32
	v_exp_f32_e32 v33, v33
	v_pk_mul_f32 v[20:21], v[28:29], v[20:21]
	v_add_f32_e32 v28, 1.0, v32
	v_add_f32_e32 v29, 1.0, v33
	v_mul_f32_e32 v32, 0xbfb8aa3b, v24
	v_mul_f32_e32 v33, 0xbfb8aa3b, v25
	v_rcp_f32_e32 v28, v28
	v_rcp_f32_e32 v29, v29
	v_exp_f32_e32 v32, v32
	v_exp_f32_e32 v33, v33
	v_pk_mul_f32 v[28:29], v[30:31], v[28:29]
	v_add_f32_e32 v30, 1.0, v32
	v_add_f32_e32 v31, 1.0, v33
	v_mul_f32_e32 v32, 0xbfb8aa3b, v26
	v_mul_f32_e32 v33, 0xbfb8aa3b, v27
	v_exp_f32_e32 v32, v32
	v_exp_f32_e32 v33, v33
	v_rcp_f32_e32 v30, v30
	v_rcp_f32_e32 v31, v31
	v_add_f32_e32 v32, 1.0, v32
	v_add_f32_e32 v33, 1.0, v33
	v_rcp_f32_e32 v32, v32
	v_rcp_f32_e32 v33, v33
	v_pk_mul_f32 v[24:25], v[24:25], v[30:31]
	v_pk_mul_f32 v[22:23], v[28:29], v[22:23]
	v_pk_mul_f32 v[24:25], v[24:25], v[16:17]
	v_pk_mul_f32 v[16:17], v[26:27], v[32:33]
	v_lshl_add_u64 v[28:29], v[34:35], 0, v[152:153]
	v_pk_mul_f32 v[26:27], v[16:17], v[18:19]
	v_cvt_pk_bf16_f32 v16, v20, v21
	v_cvt_pk_bf16_f32 v17, v22, v23
	v_cvt_pk_bf16_f32 v18, v24, v25
	v_cvt_pk_bf16_f32 v19, v26, v27
	flat_store_dwordx4 v[28:29], v[16:19] sc1
	s_nop 1
	v_mul_f32_e32 v16, 0xbfb8aa3b, v12
	v_mul_f32_e32 v17, 0xbfb8aa3b, v13
	v_exp_f32_e32 v16, v16
	v_exp_f32_e32 v17, v17
	v_add_u32_e32 v18, 0xb0, v172
	v_mad_i64_i32 v[18:19], s[10:11], v18, s2, v[128:129]
	v_add_f32_e32 v16, 1.0, v16
	v_add_f32_e32 v17, 1.0, v17
	v_rcp_f32_e32 v16, v16
	v_rcp_f32_e32 v17, v17
	v_lshl_add_u64 v[18:19], v[18:19], 0, s[8:9]
	v_pk_mul_f32 v[12:13], v[12:13], v[16:17]
	v_mul_f32_e32 v16, 0xbfb8aa3b, v14
	v_mul_f32_e32 v17, 0xbfb8aa3b, v15
	v_exp_f32_e32 v16, v16
	v_exp_f32_e32 v17, v17
	v_pk_mul_f32 v[4:5], v[12:13], v[4:5]
	v_add_f32_e32 v12, 1.0, v16
	v_add_f32_e32 v13, 1.0, v17
	v_mul_f32_e32 v16, 0xbfb8aa3b, v8
	v_mul_f32_e32 v17, 0xbfb8aa3b, v9
	v_rcp_f32_e32 v12, v12
	v_rcp_f32_e32 v13, v13
	v_exp_f32_e32 v16, v16
	v_exp_f32_e32 v17, v17
	v_pk_mul_f32 v[12:13], v[14:15], v[12:13]
	v_add_f32_e32 v14, 1.0, v16
	v_add_f32_e32 v15, 1.0, v17
	v_mul_f32_e32 v16, 0xbfb8aa3b, v10
	v_mul_f32_e32 v17, 0xbfb8aa3b, v11
	v_exp_f32_e32 v16, v16
	v_exp_f32_e32 v17, v17
	v_rcp_f32_e32 v14, v14
	v_rcp_f32_e32 v15, v15
	v_add_f32_e32 v16, 1.0, v16
	v_add_f32_e32 v17, 1.0, v17
	v_rcp_f32_e32 v16, v16
	v_rcp_f32_e32 v17, v17
	v_pk_mul_f32 v[8:9], v[8:9], v[14:15]
	v_pk_mul_f32 v[6:7], v[12:13], v[6:7]
	v_pk_mul_f32 v[8:9], v[8:9], v[0:1]
	v_pk_mul_f32 v[0:1], v[10:11], v[16:17]
	v_lshl_add_u64 v[12:13], v[18:19], 0, v[152:153]
	v_pk_mul_f32 v[10:11], v[0:1], v[2:3]
	v_cvt_pk_bf16_f32 v0, v4, v5
	v_cvt_pk_bf16_f32 v1, v6, v7
	v_cvt_pk_bf16_f32 v2, v8, v9
	v_cvt_pk_bf16_f32 v3, v10, v11
	flat_store_dwordx4 v[12:13], v[0:3] sc1
	s_branch .LBB0_535
